# merge GEMM epilogues: 6/8-deep software prefetch of gate-logit loads into spare VGPRs (de-serialised 32 load round trips per tile)
# speedup vs baseline: 1.0049x; 1.0049x over previous
; __device__ __forceinline__ float bflo(unsigned w) { return __uint_as_float(w << 16); }
; __device__ __forceinline__ float bfhi(unsigned w) { return __uint_as_float(w & 0xffff0000u); }
;     __device__ __forceinline__ void mid(f32x4 (&acc)[2][2][4][2], const Unit& u, int wr, int wc, int fr, int fq) const {
;         const int row0 = u.pm * BM + wr * 64 + fr, col0 = u.pn * BM + wc * 32 + 8 * fq;
; #pragma unroll
;         for (int ai = 0; ai < 2; ++ai)
; #pragma unroll
;             for (int m = 0; m < 4; ++m) { const bf16_t* gp = GL + (size_t)(row0 + ai * HALF + m * 16) * 2048 + col0;
; #pragma unroll
;                 for (int bj = 0; bj < 2; ++bj) { const u32x4 la = *(const u32x4*)(gp + bj * HALF), lb = *(const u32x4*)(gp + 1024 + bj * HALF);
; #pragma unroll
;                     for (int n = 0; n < 2; ++n)
; #pragma unroll
;                         for (int j = 0; j < 4; ++j) { const int e = n * 4 + j; const unsigned wa = la[e >> 1], wb = lb[e >> 1];
;                             const float a = (e & 1) ? bfhi(wa) : bflo(wa), b = (e & 1) ? bfhi(wb) : bflo(wb);
;                             acc[ai][bj][m][n][j] *= (1.0f + __expf(-b)) * __builtin_amdgcn_rcpf(1.0f + __expf(-a)); }
;                     asm volatile("" : "+v"(acc[ai][bj][m][0]), "+v"(acc[ai][bj][m][1]) :: "memory"); } }
.LBB0_384:
	v_mov_b32_e32 v130, v167
	s_lshl_b32 s1, s52, 8
	s_add_i32 s1, s1, s4
	v_and_or_b32 v154, v130, 15, s1
	s_lshl_b32 s1, s80, 8
	v_ashrrev_i32_e32 v130, 1, v130
	s_or_b32 s1, s1, s5
	v_and_b32_e32 v130, -8, v130
	v_add_u32_e32 v130, s1, v130
	v_ashrrev_i32_e32 v155, 31, v154
	v_ashrrev_i32_e32 v131, 31, v130
	v_lshlrev_b64 v[132:133], 12, v[154:155]
	v_lshl_add_u64 v[132:133], s[14:15], 0, v[132:133]
	v_lshlrev_b64 v[156:157], 1, v[130:131]
	v_lshl_add_u64 v[152:153], v[132:133], 0, v[156:157]
	v_mov_b32_e32 v178, v152
	v_mov_b32_e32 v179, v153
	v_add_co_u32_e32 v212, vcc, 0x10000, v152
	s_nop 1
	v_addc_co_u32_e32 v213, vcc, 0, v153, vcc
	v_add_co_u32_e32 v214, vcc, 0x20000, v152
	s_nop 1
	v_addc_co_u32_e32 v215, vcc, 0, v153, vcc
	v_add_co_u32_e32 v236, vcc, 0x30000, v152
	s_nop 1
	v_addc_co_u32_e32 v237, vcc, 0, v153, vcc
	v_add_co_u32_e32 v238, vcc, 0x80000, v152
	s_nop 1
	v_addc_co_u32_e32 v239, vcc, 0, v153, vcc
	v_add_co_u32_e32 v240, vcc, 0x90000, v152
	s_nop 1
	v_addc_co_u32_e32 v241, vcc, 0, v153, vcc
	v_add_co_u32_e32 v248, vcc, 0xa0000, v152
	s_nop 1
	v_addc_co_u32_e32 v249, vcc, 0, v153, vcc
	v_add_co_u32_e32 v250, vcc, 0xb0000, v152
	s_nop 1
	v_addc_co_u32_e32 v251, vcc, 0, v153, vcc
	global_load_dwordx4 v[180:183], v[178:179], off
	global_load_dwordx4 v[184:187], v[178:179], off offset:2048
	global_load_dwordx4 v[188:191], v[178:179], off offset:256
	global_load_dwordx4 v[192:195], v[178:179], off offset:2304
	global_load_dwordx4 v[196:199], v[212:213], off
	global_load_dwordx4 v[200:203], v[212:213], off offset:2048
	global_load_dwordx4 v[204:207], v[212:213], off offset:256
	global_load_dwordx4 v[208:211], v[212:213], off offset:2304
	global_load_dwordx4 v[220:223], v[214:215], off
	global_load_dwordx4 v[224:227], v[214:215], off offset:2048
	global_load_dwordx4 v[228:231], v[214:215], off offset:256
	global_load_dwordx4 v[232:235], v[214:215], off offset:2304
	s_waitcnt vmcnt(10)
	s_nop 1
	v_mov_b32_e32 v130, v180
	v_mov_b32_e32 v131, v181
	v_mov_b32_e32 v132, v182
	v_mov_b32_e32 v133, v183
	v_mov_b32_e32 v134, v184
	v_mov_b32_e32 v135, v185
	v_mov_b32_e32 v136, v186
	v_mov_b32_e32 v137, v187
	global_load_dwordx4 v[180:183], v[236:237], off
	global_load_dwordx4 v[184:187], v[236:237], off offset:2048
	s_mov_b32 s1, 0x80000
	s_mov_b64 s[20:21], 0x80000
	v_lshlrev_b32_e32 v155, 16, v130
	v_mul_f32_e32 v155, 0xbfb8aa3b, v155
	v_and_b32_e32 v130, 0xffff0000, v130
	v_exp_f32_e32 v155, v155
	v_mul_f32_e32 v130, 0xbfb8aa3b, v130
	v_exp_f32_e32 v130, v130
	v_lshlrev_b32_e32 v158, 16, v134
	v_and_b32_e32 v134, 0xffff0000, v134
	v_add_f32_e32 v155, 1.0, v155
	v_mul_f32_e32 v134, 0xbfb8aa3b, v134
	v_rcp_f32_e32 v160, v155
	v_exp_f32_e32 v159, v134
	v_add_f32_e32 v130, 1.0, v130
	v_lshlrev_b32_e32 v134, 16, v131
	v_and_b32_e32 v155, 0xffff0000, v131
	v_rcp_f32_e32 v161, v130
	v_lshlrev_b32_e32 v130, 16, v135
	v_mul_f32_e32 v134, 0xbfb8aa3b, v134
	v_and_b32_e32 v131, 0xffff0000, v135
	v_mul_f32_e32 v135, 0xbfb8aa3b, v155
	v_exp_f32_e32 v134, v134
	v_exp_f32_e32 v135, v135
	v_mul_f32_e32 v130, 0xbfb8aa3b, v130
	v_mul_f32_e32 v131, 0xbfb8aa3b, v131
	v_exp_f32_e32 v130, v130
	v_add_f32_e32 v134, 1.0, v134
	v_exp_f32_e32 v131, v131
	v_add_f32_e32 v135, 1.0, v135
	v_rcp_f32_e32 v134, v134
	v_rcp_f32_e32 v135, v135
	v_pk_add_f32 v[130:131], v[130:131], 1.0 op_sel_hi:[1,0]
	v_and_b32_e32 v155, 0xffff0000, v133
	v_mul_f32_e32 v158, 0xbfb8aa3b, v158
	v_pk_mul_f32 v[130:131], v[130:131], v[134:135]
	v_exp_f32_e32 v158, v158
	v_pk_mul_f32 v[2:3], v[2:3], v[130:131]
	v_lshlrev_b32_e32 v131, 16, v136
	v_mul_f32_e32 v131, 0xbfb8aa3b, v131
	v_lshlrev_b32_e32 v130, 16, v132
	v_exp_f32_e32 v134, v131
	v_and_b32_e32 v131, 0xffff0000, v132
	v_and_b32_e32 v132, 0xffff0000, v136
	v_mul_f32_e32 v132, 0xbfb8aa3b, v132
	v_lshlrev_b32_e32 v136, 16, v133
	v_mul_f32_e32 v130, 0xbfb8aa3b, v130
	v_exp_f32_e32 v135, v132
	v_mul_f32_e32 v131, 0xbfb8aa3b, v131
	v_lshlrev_b32_e32 v132, 16, v137
	v_mul_f32_e32 v136, 0xbfb8aa3b, v136
	v_and_b32_e32 v133, 0xffff0000, v137
	v_mul_f32_e32 v137, 0xbfb8aa3b, v155
	v_exp_f32_e32 v130, v130
	v_exp_f32_e32 v131, v131
	v_exp_f32_e32 v136, v136
	v_exp_f32_e32 v137, v137
	v_mul_f32_e32 v132, 0xbfb8aa3b, v132
	v_mul_f32_e32 v133, 0xbfb8aa3b, v133
	v_add_f32_e32 v130, 1.0, v130
	v_add_f32_e32 v131, 1.0, v131
	v_exp_f32_e32 v132, v132
	v_add_f32_e32 v136, 1.0, v136
	v_exp_f32_e32 v133, v133
	v_add_f32_e32 v137, 1.0, v137
	v_rcp_f32_e32 v130, v130
	v_rcp_f32_e32 v131, v131
	v_rcp_f32_e32 v136, v136
	v_rcp_f32_e32 v137, v137
	v_pk_add_f32 v[158:159], v[158:159], 1.0 op_sel_hi:[1,0]
	v_pk_add_f32 v[132:133], v[132:133], 1.0 op_sel_hi:[1,0]
	v_pk_add_f32 v[134:135], v[134:135], 1.0 op_sel_hi:[1,0]
	v_pk_mul_f32 v[158:159], v[158:159], v[160:161]
	v_pk_mul_f32 v[130:131], v[134:135], v[130:131]
	v_pk_mul_f32 v[132:133], v[132:133], v[136:137]
	v_pk_mul_f32 v[0:1], v[0:1], v[158:159]
	v_pk_mul_f32 v[6:7], v[6:7], v[132:133]
	v_pk_mul_f32 v[4:5], v[4:5], v[130:131]
	s_nop 0
	s_waitcnt vmcnt(10)
; __device__ __forceinline__ float bflo(unsigned w) { return __uint_as_float(w << 16); }
; __device__ __forceinline__ float bfhi(unsigned w) { return __uint_as_float(w & 0xffff0000u); }
;     __device__ __forceinline__ void mid(f32x4 (&acc)[2][2][4][2], const Unit& u, int wr, int wc, int fr, int fq) const {
;         const int row0 = u.pm * BM + wr * 64 + fr, col0 = u.pn * BM + wc * 32 + 8 * fq;
; #pragma unroll
;         for (int ai = 0; ai < 2; ++ai)
; #pragma unroll
;             for (int m = 0; m < 4; ++m) { const bf16_t* gp = GL + (size_t)(row0 + ai * HALF + m * 16) * 2048 + col0;
; #pragma unroll
;                 for (int bj = 0; bj < 2; ++bj) { const u32x4 la = *(const u32x4*)(gp + bj * HALF), lb = *(const u32x4*)(gp + 1024 + bj * HALF);
; #pragma unroll
;                     for (int n = 0; n < 2; ++n)
; #pragma unroll
;                         for (int j = 0; j < 4; ++j) { const int e = n * 4 + j; const unsigned wa = la[e >> 1], wb = lb[e >> 1];
;                             const float a = (e & 1) ? bfhi(wa) : bflo(wa), b = (e & 1) ? bfhi(wb) : bflo(wb);
;                             acc[ai][bj][m][n][j] *= (1.0f + __expf(-b)) * __builtin_amdgcn_rcpf(1.0f + __expf(-a)); }
;                     asm volatile("" : "+v"(acc[ai][bj][m][0]), "+v"(acc[ai][bj][m][1]) :: "memory"); } }
	s_nop 1
	v_mov_b32_e32 v130, v188
	v_mov_b32_e32 v131, v189
	v_mov_b32_e32 v132, v190
	v_mov_b32_e32 v133, v191
	v_mov_b32_e32 v134, v192
	v_mov_b32_e32 v135, v193
	v_mov_b32_e32 v136, v194
	v_mov_b32_e32 v137, v195
	global_load_dwordx4 v[188:191], v[236:237], off offset:256
	global_load_dwordx4 v[192:195], v[236:237], off offset:2304
	v_lshlrev_b32_e32 v155, 16, v130
	v_mul_f32_e32 v155, 0xbfb8aa3b, v155
	v_and_b32_e32 v130, 0xffff0000, v130
	v_exp_f32_e32 v155, v155
	v_mul_f32_e32 v130, 0xbfb8aa3b, v130
	v_exp_f32_e32 v130, v130
	v_lshlrev_b32_e32 v158, 16, v134
	v_and_b32_e32 v134, 0xffff0000, v134
	v_add_f32_e32 v155, 1.0, v155
	v_mul_f32_e32 v134, 0xbfb8aa3b, v134
	v_rcp_f32_e32 v160, v155
	v_exp_f32_e32 v159, v134
	v_add_f32_e32 v130, 1.0, v130
	v_lshlrev_b32_e32 v134, 16, v131
	v_and_b32_e32 v155, 0xffff0000, v131
	v_rcp_f32_e32 v161, v130
	v_lshlrev_b32_e32 v130, 16, v135
	v_mul_f32_e32 v134, 0xbfb8aa3b, v134
	v_and_b32_e32 v131, 0xffff0000, v135
	v_mul_f32_e32 v135, 0xbfb8aa3b, v155
	v_exp_f32_e32 v134, v134
	v_exp_f32_e32 v135, v135
	v_mul_f32_e32 v130, 0xbfb8aa3b, v130
	v_mul_f32_e32 v131, 0xbfb8aa3b, v131
	v_exp_f32_e32 v130, v130
	v_add_f32_e32 v134, 1.0, v134
	v_exp_f32_e32 v131, v131
	v_add_f32_e32 v135, 1.0, v135
	v_rcp_f32_e32 v134, v134
	v_rcp_f32_e32 v135, v135
	v_pk_add_f32 v[130:131], v[130:131], 1.0 op_sel_hi:[1,0]
	v_and_b32_e32 v155, 0xffff0000, v133
	v_mul_f32_e32 v158, 0xbfb8aa3b, v158
	v_pk_mul_f32 v[130:131], v[130:131], v[134:135]
	v_exp_f32_e32 v158, v158
	v_pk_mul_f32 v[10:11], v[10:11], v[130:131]
	v_lshlrev_b32_e32 v131, 16, v132
	v_mul_f32_e32 v131, 0xbfb8aa3b, v131
	v_and_b32_e32 v132, 0xffff0000, v132
	v_exp_f32_e32 v131, v131
	v_mul_f32_e32 v132, 0xbfb8aa3b, v132
	v_exp_f32_e32 v132, v132
	v_lshlrev_b32_e32 v130, 16, v136
	v_add_f32_e32 v131, 1.0, v131
	v_rcp_f32_e32 v134, v131
	v_and_b32_e32 v131, 0xffff0000, v136
	v_add_f32_e32 v132, 1.0, v132
	v_lshlrev_b32_e32 v136, 16, v133
	v_rcp_f32_e32 v135, v132
	v_lshlrev_b32_e32 v132, 16, v137
	v_mul_f32_e32 v136, 0xbfb8aa3b, v136
	v_and_b32_e32 v133, 0xffff0000, v137
	v_mul_f32_e32 v137, 0xbfb8aa3b, v155
	v_mul_f32_e32 v130, 0xbfb8aa3b, v130
	v_mul_f32_e32 v131, 0xbfb8aa3b, v131
	v_exp_f32_e32 v136, v136
	v_exp_f32_e32 v137, v137
	v_exp_f32_e32 v130, v130
	v_exp_f32_e32 v131, v131
	v_mul_f32_e32 v132, 0xbfb8aa3b, v132
	v_mul_f32_e32 v133, 0xbfb8aa3b, v133
	v_exp_f32_e32 v132, v132
	v_add_f32_e32 v136, 1.0, v136
	v_exp_f32_e32 v133, v133
	v_add_f32_e32 v137, 1.0, v137
	v_rcp_f32_e32 v136, v136
	v_rcp_f32_e32 v137, v137
	v_pk_add_f32 v[130:131], v[130:131], 1.0 op_sel_hi:[1,0]
	v_pk_add_f32 v[158:159], v[158:159], 1.0 op_sel_hi:[1,0]
	v_pk_mul_f32 v[130:131], v[130:131], v[134:135]
	v_pk_add_f32 v[132:133], v[132:133], 1.0 op_sel_hi:[1,0]
	v_pk_mul_f32 v[12:13], v[12:13], v[130:131]
	v_or_b32_e32 v130, 16, v154
	v_ashrrev_i32_e32 v131, 31, v130
	v_pk_mul_f32 v[158:159], v[158:159], v[160:161]
	v_pk_mul_f32 v[132:133], v[132:133], v[136:137]
	v_lshlrev_b64 v[130:131], 12, v[130:131]
	v_pk_mul_f32 v[8:9], v[8:9], v[158:159]
	v_pk_mul_f32 v[14:15], v[14:15], v[132:133]
	v_lshl_add_u64 v[130:131], s[14:15], 0, v[130:131]
	v_lshl_add_u64 v[158:159], v[130:131], 0, v[156:157]
	s_waitcnt vmcnt(10)
	s_nop 1
	v_mov_b32_e32 v130, v196
	v_mov_b32_e32 v131, v197
	v_mov_b32_e32 v132, v198
	v_mov_b32_e32 v133, v199
	v_mov_b32_e32 v134, v200
	v_mov_b32_e32 v135, v201
	v_mov_b32_e32 v136, v202
	v_mov_b32_e32 v137, v203
	global_load_dwordx4 v[196:199], v[238:239], off
	global_load_dwordx4 v[200:203], v[238:239], off offset:2048
	v_lshlrev_b32_e32 v155, 16, v130
	v_mul_f32_e32 v155, 0xbfb8aa3b, v155
	v_and_b32_e32 v130, 0xffff0000, v130
	v_exp_f32_e32 v155, v155
	v_mul_f32_e32 v130, 0xbfb8aa3b, v130
	v_exp_f32_e32 v130, v130
	v_lshlrev_b32_e32 v160, 16, v134
	v_and_b32_e32 v134, 0xffff0000, v134
	v_add_f32_e32 v155, 1.0, v155
	v_mul_f32_e32 v134, 0xbfb8aa3b, v134
	v_rcp_f32_e32 v162, v155
	v_exp_f32_e32 v161, v134
	v_add_f32_e32 v130, 1.0, v130
	v_lshlrev_b32_e32 v134, 16, v131
	v_and_b32_e32 v155, 0xffff0000, v131
	v_rcp_f32_e32 v163, v130
	v_lshlrev_b32_e32 v130, 16, v135
	v_mul_f32_e32 v134, 0xbfb8aa3b, v134
	v_and_b32_e32 v131, 0xffff0000, v135
	v_mul_f32_e32 v135, 0xbfb8aa3b, v155
	v_exp_f32_e32 v134, v134
	v_exp_f32_e32 v135, v135
	v_mul_f32_e32 v130, 0xbfb8aa3b, v130
	v_mul_f32_e32 v131, 0xbfb8aa3b, v131
	v_exp_f32_e32 v130, v130
	v_add_f32_e32 v134, 1.0, v134
	v_exp_f32_e32 v131, v131
	v_add_f32_e32 v135, 1.0, v135
	v_rcp_f32_e32 v134, v134
	v_rcp_f32_e32 v135, v135
	v_pk_add_f32 v[130:131], v[130:131], 1.0 op_sel_hi:[1,0]
	v_and_b32_e32 v155, 0xffff0000, v133
	v_mul_f32_e32 v160, 0xbfb8aa3b, v160
	v_pk_mul_f32 v[130:131], v[130:131], v[134:135]
	v_exp_f32_e32 v160, v160
	v_pk_mul_f32 v[18:19], v[18:19], v[130:131]
	v_lshlrev_b32_e32 v131, 16, v136
	v_mul_f32_e32 v131, 0xbfb8aa3b, v131
	v_lshlrev_b32_e32 v130, 16, v132
	v_exp_f32_e32 v134, v131
	v_and_b32_e32 v131, 0xffff0000, v132
	v_and_b32_e32 v132, 0xffff0000, v136
	v_mul_f32_e32 v132, 0xbfb8aa3b, v132
	v_lshlrev_b32_e32 v136, 16, v133
	v_mul_f32_e32 v130, 0xbfb8aa3b, v130
	v_exp_f32_e32 v135, v132
	v_mul_f32_e32 v131, 0xbfb8aa3b, v131
	v_lshlrev_b32_e32 v132, 16, v137
	v_mul_f32_e32 v136, 0xbfb8aa3b, v136
	v_and_b32_e32 v133, 0xffff0000, v137
	v_mul_f32_e32 v137, 0xbfb8aa3b, v155
	v_exp_f32_e32 v130, v130
	v_exp_f32_e32 v131, v131
	v_exp_f32_e32 v136, v136
	v_exp_f32_e32 v137, v137
	v_mul_f32_e32 v132, 0xbfb8aa3b, v132
	v_mul_f32_e32 v133, 0xbfb8aa3b, v133
	v_add_f32_e32 v130, 1.0, v130
	v_add_f32_e32 v131, 1.0, v131
	v_exp_f32_e32 v132, v132
	v_add_f32_e32 v136, 1.0, v136
	v_exp_f32_e32 v133, v133
	v_add_f32_e32 v137, 1.0, v137
	v_rcp_f32_e32 v130, v130
	v_rcp_f32_e32 v131, v131
	v_rcp_f32_e32 v136, v136
	v_rcp_f32_e32 v137, v137
	v_pk_add_f32 v[160:161], v[160:161], 1.0 op_sel_hi:[1,0]
	v_pk_add_f32 v[132:133], v[132:133], 1.0 op_sel_hi:[1,0]
	v_pk_add_f32 v[134:135], v[134:135], 1.0 op_sel_hi:[1,0]
	v_pk_mul_f32 v[160:161], v[160:161], v[162:163]
	v_pk_mul_f32 v[130:131], v[134:135], v[130:131]
	v_pk_mul_f32 v[132:133], v[132:133], v[136:137]
	v_pk_mul_f32 v[16:17], v[16:17], v[160:161]
	v_pk_mul_f32 v[22:23], v[22:23], v[132:133]
	v_pk_mul_f32 v[20:21], v[20:21], v[130:131]
	s_nop 0
	s_waitcnt vmcnt(10)
; __device__ __forceinline__ float bflo(unsigned w) { return __uint_as_float(w << 16); }
; __device__ __forceinline__ float bfhi(unsigned w) { return __uint_as_float(w & 0xffff0000u); }
;     __device__ __forceinline__ void mid(f32x4 (&acc)[2][2][4][2], const Unit& u, int wr, int wc, int fr, int fq) const {
;         const int row0 = u.pm * BM + wr * 64 + fr, col0 = u.pn * BM + wc * 32 + 8 * fq;
; #pragma unroll
;         for (int ai = 0; ai < 2; ++ai)
; #pragma unroll
;             for (int m = 0; m < 4; ++m) { const bf16_t* gp = GL + (size_t)(row0 + ai * HALF + m * 16) * 2048 + col0;
; #pragma unroll
;                 for (int bj = 0; bj < 2; ++bj) { const u32x4 la = *(const u32x4*)(gp + bj * HALF), lb = *(const u32x4*)(gp + 1024 + bj * HALF);
; #pragma unroll
;                     for (int n = 0; n < 2; ++n)
; #pragma unroll
;                         for (int j = 0; j < 4; ++j) { const int e = n * 4 + j; const unsigned wa = la[e >> 1], wb = lb[e >> 1];
;                             const float a = (e & 1) ? bfhi(wa) : bflo(wa), b = (e & 1) ? bfhi(wb) : bflo(wb);
;                             acc[ai][bj][m][n][j] *= (1.0f + __expf(-b)) * __builtin_amdgcn_rcpf(1.0f + __expf(-a)); }
;                     asm volatile("" : "+v"(acc[ai][bj][m][0]), "+v"(acc[ai][bj][m][1]) :: "memory"); } }
	s_nop 1
	v_mov_b32_e32 v130, v204
	v_mov_b32_e32 v131, v205
	v_mov_b32_e32 v132, v206
	v_mov_b32_e32 v133, v207
	v_mov_b32_e32 v134, v208
	v_mov_b32_e32 v135, v209
	v_mov_b32_e32 v136, v210
	v_mov_b32_e32 v137, v211
	global_load_dwordx4 v[204:207], v[238:239], off offset:256
	global_load_dwordx4 v[208:211], v[238:239], off offset:2304
	v_lshlrev_b32_e32 v155, 16, v130
	v_mul_f32_e32 v155, 0xbfb8aa3b, v155
	v_and_b32_e32 v130, 0xffff0000, v130
	v_exp_f32_e32 v155, v155
	v_mul_f32_e32 v130, 0xbfb8aa3b, v130
	v_exp_f32_e32 v130, v130
	v_lshlrev_b32_e32 v158, 16, v134
	v_and_b32_e32 v134, 0xffff0000, v134
	v_add_f32_e32 v155, 1.0, v155
	v_mul_f32_e32 v134, 0xbfb8aa3b, v134
	v_rcp_f32_e32 v160, v155
	v_exp_f32_e32 v159, v134
	v_add_f32_e32 v130, 1.0, v130
	v_lshlrev_b32_e32 v134, 16, v131
	v_and_b32_e32 v155, 0xffff0000, v131
	v_rcp_f32_e32 v161, v130
	v_lshlrev_b32_e32 v130, 16, v135
	v_mul_f32_e32 v134, 0xbfb8aa3b, v134
	v_and_b32_e32 v131, 0xffff0000, v135
	v_mul_f32_e32 v135, 0xbfb8aa3b, v155
	v_exp_f32_e32 v134, v134
	v_exp_f32_e32 v135, v135
	v_mul_f32_e32 v130, 0xbfb8aa3b, v130
	v_mul_f32_e32 v131, 0xbfb8aa3b, v131
	v_exp_f32_e32 v130, v130
	v_add_f32_e32 v134, 1.0, v134
	v_exp_f32_e32 v131, v131
	v_add_f32_e32 v135, 1.0, v135
	v_rcp_f32_e32 v134, v134
	v_rcp_f32_e32 v135, v135
	v_pk_add_f32 v[130:131], v[130:131], 1.0 op_sel_hi:[1,0]
	v_and_b32_e32 v155, 0xffff0000, v133
	v_mul_f32_e32 v158, 0xbfb8aa3b, v158
	v_pk_mul_f32 v[130:131], v[130:131], v[134:135]
	v_exp_f32_e32 v158, v158
	v_pk_mul_f32 v[26:27], v[26:27], v[130:131]
	v_lshlrev_b32_e32 v131, 16, v132
	v_mul_f32_e32 v131, 0xbfb8aa3b, v131
	v_and_b32_e32 v132, 0xffff0000, v132
	v_exp_f32_e32 v131, v131
	v_mul_f32_e32 v132, 0xbfb8aa3b, v132
	v_exp_f32_e32 v132, v132
	v_lshlrev_b32_e32 v130, 16, v136
	v_add_f32_e32 v131, 1.0, v131
	v_rcp_f32_e32 v134, v131
	v_and_b32_e32 v131, 0xffff0000, v136
	v_add_f32_e32 v132, 1.0, v132
	v_lshlrev_b32_e32 v136, 16, v133
	v_rcp_f32_e32 v135, v132
	v_lshlrev_b32_e32 v132, 16, v137
	v_mul_f32_e32 v136, 0xbfb8aa3b, v136
	v_and_b32_e32 v133, 0xffff0000, v137
	v_mul_f32_e32 v137, 0xbfb8aa3b, v155
	v_mul_f32_e32 v130, 0xbfb8aa3b, v130
	v_mul_f32_e32 v131, 0xbfb8aa3b, v131
	v_exp_f32_e32 v136, v136
	v_exp_f32_e32 v137, v137
	v_exp_f32_e32 v130, v130
	v_exp_f32_e32 v131, v131
	v_mul_f32_e32 v132, 0xbfb8aa3b, v132
	v_mul_f32_e32 v133, 0xbfb8aa3b, v133
	v_exp_f32_e32 v132, v132
	v_add_f32_e32 v136, 1.0, v136
	v_exp_f32_e32 v133, v133
	v_add_f32_e32 v137, 1.0, v137
	v_rcp_f32_e32 v136, v136
	v_rcp_f32_e32 v137, v137
	v_pk_add_f32 v[130:131], v[130:131], 1.0 op_sel_hi:[1,0]
	v_pk_add_f32 v[158:159], v[158:159], 1.0 op_sel_hi:[1,0]
	v_pk_mul_f32 v[130:131], v[130:131], v[134:135]
	v_pk_add_f32 v[132:133], v[132:133], 1.0 op_sel_hi:[1,0]
	v_pk_mul_f32 v[28:29], v[28:29], v[130:131]
	v_or_b32_e32 v130, 32, v154
	v_ashrrev_i32_e32 v131, 31, v130
	v_pk_mul_f32 v[158:159], v[158:159], v[160:161]
	v_pk_mul_f32 v[132:133], v[132:133], v[136:137]
	v_lshlrev_b64 v[130:131], 12, v[130:131]
	v_pk_mul_f32 v[24:25], v[24:25], v[158:159]
	v_pk_mul_f32 v[30:31], v[30:31], v[132:133]
	v_lshl_add_u64 v[130:131], s[14:15], 0, v[130:131]
	v_lshl_add_u64 v[158:159], v[130:131], 0, v[156:157]
	s_waitcnt vmcnt(10)
	s_nop 1
	v_mov_b32_e32 v130, v220
	v_mov_b32_e32 v131, v221
	v_mov_b32_e32 v132, v222
	v_mov_b32_e32 v133, v223
	v_mov_b32_e32 v134, v224
	v_mov_b32_e32 v135, v225
	v_mov_b32_e32 v136, v226
	v_mov_b32_e32 v137, v227
	global_load_dwordx4 v[220:223], v[240:241], off
	global_load_dwordx4 v[224:227], v[240:241], off offset:2048
	v_lshlrev_b32_e32 v155, 16, v130
	v_mul_f32_e32 v155, 0xbfb8aa3b, v155
	v_and_b32_e32 v130, 0xffff0000, v130
	v_exp_f32_e32 v155, v155
	v_mul_f32_e32 v130, 0xbfb8aa3b, v130
	v_exp_f32_e32 v130, v130
	v_lshlrev_b32_e32 v160, 16, v134
	v_and_b32_e32 v134, 0xffff0000, v134
	v_add_f32_e32 v155, 1.0, v155
	v_mul_f32_e32 v134, 0xbfb8aa3b, v134
	v_rcp_f32_e32 v162, v155
	v_exp_f32_e32 v161, v134
	v_add_f32_e32 v130, 1.0, v130
	v_lshlrev_b32_e32 v134, 16, v131
	v_and_b32_e32 v155, 0xffff0000, v131
	v_rcp_f32_e32 v163, v130
	v_lshlrev_b32_e32 v130, 16, v135
	v_mul_f32_e32 v134, 0xbfb8aa3b, v134
	v_and_b32_e32 v131, 0xffff0000, v135
	v_mul_f32_e32 v135, 0xbfb8aa3b, v155
	v_exp_f32_e32 v134, v134
	v_exp_f32_e32 v135, v135
	v_mul_f32_e32 v130, 0xbfb8aa3b, v130
	v_mul_f32_e32 v131, 0xbfb8aa3b, v131
	v_exp_f32_e32 v130, v130
	v_add_f32_e32 v134, 1.0, v134
	v_exp_f32_e32 v131, v131
	v_add_f32_e32 v135, 1.0, v135
	v_rcp_f32_e32 v134, v134
	v_rcp_f32_e32 v135, v135
	v_pk_add_f32 v[130:131], v[130:131], 1.0 op_sel_hi:[1,0]
	v_and_b32_e32 v155, 0xffff0000, v133
	v_mul_f32_e32 v160, 0xbfb8aa3b, v160
	v_pk_mul_f32 v[130:131], v[130:131], v[134:135]
	v_exp_f32_e32 v160, v160
	v_pk_mul_f32 v[48:49], v[48:49], v[130:131]
	v_lshlrev_b32_e32 v131, 16, v136
	v_mul_f32_e32 v131, 0xbfb8aa3b, v131
	v_lshlrev_b32_e32 v130, 16, v132
	v_exp_f32_e32 v134, v131
	v_and_b32_e32 v131, 0xffff0000, v132
	v_and_b32_e32 v132, 0xffff0000, v136
	v_mul_f32_e32 v132, 0xbfb8aa3b, v132
	v_lshlrev_b32_e32 v136, 16, v133
	v_mul_f32_e32 v130, 0xbfb8aa3b, v130
	v_exp_f32_e32 v135, v132
	v_mul_f32_e32 v131, 0xbfb8aa3b, v131
	v_lshlrev_b32_e32 v132, 16, v137
	v_mul_f32_e32 v136, 0xbfb8aa3b, v136
	v_and_b32_e32 v133, 0xffff0000, v137
	v_mul_f32_e32 v137, 0xbfb8aa3b, v155
	v_exp_f32_e32 v130, v130
	v_exp_f32_e32 v131, v131
	v_exp_f32_e32 v136, v136
	v_exp_f32_e32 v137, v137
	v_mul_f32_e32 v132, 0xbfb8aa3b, v132
	v_mul_f32_e32 v133, 0xbfb8aa3b, v133
	v_add_f32_e32 v130, 1.0, v130
	v_add_f32_e32 v131, 1.0, v131
	v_exp_f32_e32 v132, v132
	v_add_f32_e32 v136, 1.0, v136
	v_exp_f32_e32 v133, v133
	v_add_f32_e32 v137, 1.0, v137
	v_rcp_f32_e32 v130, v130
	v_rcp_f32_e32 v131, v131
	v_rcp_f32_e32 v136, v136
	v_rcp_f32_e32 v137, v137
	v_pk_add_f32 v[160:161], v[160:161], 1.0 op_sel_hi:[1,0]
	v_pk_add_f32 v[132:133], v[132:133], 1.0 op_sel_hi:[1,0]
	v_pk_add_f32 v[134:135], v[134:135], 1.0 op_sel_hi:[1,0]
	v_pk_mul_f32 v[160:161], v[160:161], v[162:163]
	v_pk_mul_f32 v[130:131], v[134:135], v[130:131]
	v_pk_mul_f32 v[132:133], v[132:133], v[136:137]
	v_pk_mul_f32 v[46:47], v[46:47], v[160:161]
	v_pk_mul_f32 v[52:53], v[52:53], v[132:133]
	v_pk_mul_f32 v[50:51], v[50:51], v[130:131]
	s_nop 0
	s_waitcnt vmcnt(10)
; __device__ __forceinline__ float bflo(unsigned w) { return __uint_as_float(w << 16); }
; __device__ __forceinline__ float bfhi(unsigned w) { return __uint_as_float(w & 0xffff0000u); }
;     __device__ __forceinline__ void mid(f32x4 (&acc)[2][2][4][2], const Unit& u, int wr, int wc, int fr, int fq) const {
;         const int row0 = u.pm * BM + wr * 64 + fr, col0 = u.pn * BM + wc * 32 + 8 * fq;
; #pragma unroll
;         for (int ai = 0; ai < 2; ++ai)
; #pragma unroll
;             for (int m = 0; m < 4; ++m) { const bf16_t* gp = GL + (size_t)(row0 + ai * HALF + m * 16) * 2048 + col0;
; #pragma unroll
;                 for (int bj = 0; bj < 2; ++bj) { const u32x4 la = *(const u32x4*)(gp + bj * HALF), lb = *(const u32x4*)(gp + 1024 + bj * HALF);
; #pragma unroll
;                     for (int n = 0; n < 2; ++n)
; #pragma unroll
;                         for (int j = 0; j < 4; ++j) { const int e = n * 4 + j; const unsigned wa = la[e >> 1], wb = lb[e >> 1];
;                             const float a = (e & 1) ? bfhi(wa) : bflo(wa), b = (e & 1) ? bfhi(wb) : bflo(wb);
;                             acc[ai][bj][m][n][j] *= (1.0f + __expf(-b)) * __builtin_amdgcn_rcpf(1.0f + __expf(-a)); }
;                     asm volatile("" : "+v"(acc[ai][bj][m][0]), "+v"(acc[ai][bj][m][1]) :: "memory"); } }
	s_nop 1
	v_mov_b32_e32 v130, v228
	v_mov_b32_e32 v131, v229
	v_mov_b32_e32 v132, v230
	v_mov_b32_e32 v133, v231
	v_mov_b32_e32 v134, v232
	v_mov_b32_e32 v135, v233
	v_mov_b32_e32 v136, v234
	v_mov_b32_e32 v137, v235
	global_load_dwordx4 v[228:231], v[240:241], off offset:256
	global_load_dwordx4 v[232:235], v[240:241], off offset:2304
	v_lshlrev_b32_e32 v155, 16, v130
	v_mul_f32_e32 v155, 0xbfb8aa3b, v155
	v_and_b32_e32 v130, 0xffff0000, v130
	v_exp_f32_e32 v155, v155
	v_mul_f32_e32 v130, 0xbfb8aa3b, v130
	v_exp_f32_e32 v130, v130
	v_lshlrev_b32_e32 v158, 16, v134
	v_and_b32_e32 v134, 0xffff0000, v134
	v_add_f32_e32 v155, 1.0, v155
	v_mul_f32_e32 v134, 0xbfb8aa3b, v134
	v_rcp_f32_e32 v160, v155
	v_exp_f32_e32 v159, v134
	v_add_f32_e32 v130, 1.0, v130
	v_lshlrev_b32_e32 v134, 16, v131
	v_and_b32_e32 v155, 0xffff0000, v131
	v_rcp_f32_e32 v161, v130
	v_lshlrev_b32_e32 v130, 16, v135
	v_mul_f32_e32 v134, 0xbfb8aa3b, v134
	v_and_b32_e32 v131, 0xffff0000, v135
	v_mul_f32_e32 v135, 0xbfb8aa3b, v155
	v_exp_f32_e32 v134, v134
	v_exp_f32_e32 v135, v135
	v_mul_f32_e32 v130, 0xbfb8aa3b, v130
	v_mul_f32_e32 v131, 0xbfb8aa3b, v131
	v_exp_f32_e32 v130, v130
	v_add_f32_e32 v134, 1.0, v134
	v_exp_f32_e32 v131, v131
	v_add_f32_e32 v135, 1.0, v135
	v_rcp_f32_e32 v134, v134
	v_rcp_f32_e32 v135, v135
	v_pk_add_f32 v[130:131], v[130:131], 1.0 op_sel_hi:[1,0]
	v_and_b32_e32 v155, 0xffff0000, v133
	v_mul_f32_e32 v158, 0xbfb8aa3b, v158
	v_pk_mul_f32 v[130:131], v[130:131], v[134:135]
	v_exp_f32_e32 v158, v158
	v_pk_mul_f32 v[56:57], v[56:57], v[130:131]
	v_lshlrev_b32_e32 v131, 16, v132
	v_mul_f32_e32 v131, 0xbfb8aa3b, v131
	v_and_b32_e32 v132, 0xffff0000, v132
	v_exp_f32_e32 v131, v131
	v_mul_f32_e32 v132, 0xbfb8aa3b, v132
	v_exp_f32_e32 v132, v132
	v_lshlrev_b32_e32 v130, 16, v136
	v_add_f32_e32 v131, 1.0, v131
	v_rcp_f32_e32 v134, v131
	v_and_b32_e32 v131, 0xffff0000, v136
	v_add_f32_e32 v132, 1.0, v132
	v_lshlrev_b32_e32 v136, 16, v133
	v_rcp_f32_e32 v135, v132
	v_lshlrev_b32_e32 v132, 16, v137
	v_mul_f32_e32 v136, 0xbfb8aa3b, v136
	v_and_b32_e32 v133, 0xffff0000, v137
	v_mul_f32_e32 v137, 0xbfb8aa3b, v155
	v_mul_f32_e32 v130, 0xbfb8aa3b, v130
	v_mul_f32_e32 v131, 0xbfb8aa3b, v131
	v_exp_f32_e32 v136, v136
	v_exp_f32_e32 v137, v137
	v_exp_f32_e32 v130, v130
	v_exp_f32_e32 v131, v131
	v_mul_f32_e32 v132, 0xbfb8aa3b, v132
	v_mul_f32_e32 v133, 0xbfb8aa3b, v133
	v_exp_f32_e32 v132, v132
	v_add_f32_e32 v136, 1.0, v136
	v_exp_f32_e32 v133, v133
	v_add_f32_e32 v137, 1.0, v137
	v_rcp_f32_e32 v136, v136
	v_rcp_f32_e32 v137, v137
	v_pk_add_f32 v[130:131], v[130:131], 1.0 op_sel_hi:[1,0]
	v_pk_add_f32 v[158:159], v[158:159], 1.0 op_sel_hi:[1,0]
	v_pk_mul_f32 v[130:131], v[130:131], v[134:135]
	v_pk_add_f32 v[132:133], v[132:133], 1.0 op_sel_hi:[1,0]
	v_pk_mul_f32 v[58:59], v[58:59], v[130:131]
	v_or_b32_e32 v130, 48, v154
	v_ashrrev_i32_e32 v131, 31, v130
	v_pk_mul_f32 v[158:159], v[158:159], v[160:161]
	v_pk_mul_f32 v[132:133], v[132:133], v[136:137]
	v_lshlrev_b64 v[130:131], 12, v[130:131]
	v_pk_mul_f32 v[54:55], v[54:55], v[158:159]
	v_pk_mul_f32 v[60:61], v[60:61], v[132:133]
	v_lshl_add_u64 v[130:131], s[14:15], 0, v[130:131]
	v_lshl_add_u64 v[154:155], v[130:131], 0, v[156:157]
	s_waitcnt vmcnt(10)
	s_nop 1
	v_mov_b32_e32 v130, v180
	v_mov_b32_e32 v131, v181
	v_mov_b32_e32 v132, v182
	v_mov_b32_e32 v133, v183
	v_mov_b32_e32 v134, v184
	v_mov_b32_e32 v135, v185
	v_mov_b32_e32 v136, v186
	v_mov_b32_e32 v137, v187
	global_load_dwordx4 v[180:183], v[248:249], off
	global_load_dwordx4 v[184:187], v[248:249], off offset:2048
	v_lshlrev_b32_e32 v157, 16, v130
	v_mul_f32_e32 v157, 0xbfb8aa3b, v157
	v_and_b32_e32 v130, 0xffff0000, v130
	v_exp_f32_e32 v157, v157
	v_mul_f32_e32 v130, 0xbfb8aa3b, v130
	v_exp_f32_e32 v130, v130
	v_lshlrev_b32_e32 v156, 16, v134
	v_and_b32_e32 v134, 0xffff0000, v134
	v_add_f32_e32 v157, 1.0, v157
	v_mul_f32_e32 v134, 0xbfb8aa3b, v134
	v_rcp_f32_e32 v158, v157
	v_exp_f32_e32 v157, v134
	v_add_f32_e32 v130, 1.0, v130
	v_lshlrev_b32_e32 v134, 16, v131
	v_and_b32_e32 v160, 0xffff0000, v131
	v_rcp_f32_e32 v159, v130
	v_lshlrev_b32_e32 v130, 16, v135
	v_mul_f32_e32 v134, 0xbfb8aa3b, v134
	v_and_b32_e32 v131, 0xffff0000, v135
	v_mul_f32_e32 v135, 0xbfb8aa3b, v160
	v_exp_f32_e32 v134, v134
	v_exp_f32_e32 v135, v135
	v_mul_f32_e32 v130, 0xbfb8aa3b, v130
	v_mul_f32_e32 v131, 0xbfb8aa3b, v131
	v_exp_f32_e32 v130, v130
	v_add_f32_e32 v134, 1.0, v134
	v_exp_f32_e32 v131, v131
	v_add_f32_e32 v135, 1.0, v135
	v_rcp_f32_e32 v134, v134
	v_rcp_f32_e32 v135, v135
	v_mul_f32_e32 v156, 0xbfb8aa3b, v156
	v_exp_f32_e32 v156, v156
	v_pk_add_f32 v[130:131], v[130:131], 1.0 op_sel_hi:[1,0]
	v_pk_add_f32 v[156:157], v[156:157], 1.0 op_sel_hi:[1,0]
	v_pk_mul_f32 v[130:131], v[130:131], v[134:135]
	v_pk_mul_f32 v[156:157], v[156:157], v[158:159]
	v_pk_mul_f32 v[68:69], v[68:69], v[130:131]
	v_lshlrev_b32_e32 v131, 16, v136
	v_mul_f32_e32 v131, 0xbfb8aa3b, v131
	v_lshlrev_b32_e32 v130, 16, v132
	v_exp_f32_e32 v134, v131
	v_and_b32_e32 v131, 0xffff0000, v132
	v_and_b32_e32 v132, 0xffff0000, v136
	v_pk_mul_f32 v[66:67], v[66:67], v[156:157]
	v_mul_f32_e32 v132, 0xbfb8aa3b, v132
	v_lshlrev_b32_e32 v136, 16, v133
	v_and_b32_e32 v156, 0xffff0000, v133
	v_mul_f32_e32 v130, 0xbfb8aa3b, v130
	v_exp_f32_e32 v135, v132
	v_mul_f32_e32 v131, 0xbfb8aa3b, v131
	v_lshlrev_b32_e32 v132, 16, v137
	v_mul_f32_e32 v136, 0xbfb8aa3b, v136
	v_and_b32_e32 v133, 0xffff0000, v137
	v_mul_f32_e32 v137, 0xbfb8aa3b, v156
	v_exp_f32_e32 v130, v130
	v_exp_f32_e32 v131, v131
	v_exp_f32_e32 v136, v136
	v_exp_f32_e32 v137, v137
	v_mul_f32_e32 v132, 0xbfb8aa3b, v132
	v_mul_f32_e32 v133, 0xbfb8aa3b, v133
	v_add_f32_e32 v130, 1.0, v130
	v_add_f32_e32 v131, 1.0, v131
	v_exp_f32_e32 v132, v132
	v_add_f32_e32 v136, 1.0, v136
	v_exp_f32_e32 v133, v133
	v_add_f32_e32 v137, 1.0, v137
	v_rcp_f32_e32 v130, v130
	v_rcp_f32_e32 v131, v131
	v_rcp_f32_e32 v136, v136
	v_rcp_f32_e32 v137, v137
	v_pk_add_f32 v[132:133], v[132:133], 1.0 op_sel_hi:[1,0]
	v_pk_add_f32 v[134:135], v[134:135], 1.0 op_sel_hi:[1,0]
	v_pk_mul_f32 v[132:133], v[132:133], v[136:137]
	v_pk_mul_f32 v[130:131], v[134:135], v[130:131]
	v_pk_mul_f32 v[72:73], v[72:73], v[132:133]
	v_pk_mul_f32 v[70:71], v[70:71], v[130:131]
	s_nop 0
	s_waitcnt vmcnt(10)
; __device__ __forceinline__ float bflo(unsigned w) { return __uint_as_float(w << 16); }
; __device__ __forceinline__ float bfhi(unsigned w) { return __uint_as_float(w & 0xffff0000u); }
;     __device__ __forceinline__ void mid(f32x4 (&acc)[2][2][4][2], const Unit& u, int wr, int wc, int fr, int fq) const {
;         const int row0 = u.pm * BM + wr * 64 + fr, col0 = u.pn * BM + wc * 32 + 8 * fq;
; #pragma unroll
;         for (int ai = 0; ai < 2; ++ai)
; #pragma unroll
;             for (int m = 0; m < 4; ++m) { const bf16_t* gp = GL + (size_t)(row0 + ai * HALF + m * 16) * 2048 + col0;
; #pragma unroll
;                 for (int bj = 0; bj < 2; ++bj) { const u32x4 la = *(const u32x4*)(gp + bj * HALF), lb = *(const u32x4*)(gp + 1024 + bj * HALF);
; #pragma unroll
;                     for (int n = 0; n < 2; ++n)
; #pragma unroll
;                         for (int j = 0; j < 4; ++j) { const int e = n * 4 + j; const unsigned wa = la[e >> 1], wb = lb[e >> 1];
;                             const float a = (e & 1) ? bfhi(wa) : bflo(wa), b = (e & 1) ? bfhi(wb) : bflo(wb);
;                             acc[ai][bj][m][n][j] *= (1.0f + __expf(-b)) * __builtin_amdgcn_rcpf(1.0f + __expf(-a)); }
;                     asm volatile("" : "+v"(acc[ai][bj][m][0]), "+v"(acc[ai][bj][m][1]) :: "memory"); } }
	s_nop 1
	v_mov_b32_e32 v130, v188
	v_mov_b32_e32 v131, v189
	v_mov_b32_e32 v132, v190
	v_mov_b32_e32 v133, v191
	v_mov_b32_e32 v134, v192
	v_mov_b32_e32 v135, v193
	v_mov_b32_e32 v136, v194
	v_mov_b32_e32 v137, v195
	global_load_dwordx4 v[188:191], v[248:249], off offset:256
	global_load_dwordx4 v[192:195], v[248:249], off offset:2304
	v_lshlrev_b32_e32 v155, 16, v130
	v_mul_f32_e32 v155, 0xbfb8aa3b, v155
	v_and_b32_e32 v130, 0xffff0000, v130
	v_exp_f32_e32 v155, v155
	v_mul_f32_e32 v130, 0xbfb8aa3b, v130
	v_exp_f32_e32 v130, v130
	v_lshlrev_b32_e32 v154, 16, v134
	v_and_b32_e32 v134, 0xffff0000, v134
	v_add_f32_e32 v155, 1.0, v155
	v_mul_f32_e32 v134, 0xbfb8aa3b, v134
	v_rcp_f32_e32 v156, v155
	v_exp_f32_e32 v155, v134
	v_add_f32_e32 v130, 1.0, v130
	v_lshlrev_b32_e32 v134, 16, v131
	v_and_b32_e32 v158, 0xffff0000, v131
	v_rcp_f32_e32 v157, v130
	v_lshlrev_b32_e32 v130, 16, v135
	v_mul_f32_e32 v134, 0xbfb8aa3b, v134
	v_and_b32_e32 v131, 0xffff0000, v135
	v_mul_f32_e32 v135, 0xbfb8aa3b, v158
	v_exp_f32_e32 v134, v134
	v_exp_f32_e32 v135, v135
	v_mul_f32_e32 v130, 0xbfb8aa3b, v130
	v_mul_f32_e32 v131, 0xbfb8aa3b, v131
	v_exp_f32_e32 v130, v130
	v_add_f32_e32 v134, 1.0, v134
	v_exp_f32_e32 v131, v131
	v_add_f32_e32 v135, 1.0, v135
	v_rcp_f32_e32 v134, v134
	v_rcp_f32_e32 v135, v135
	v_pk_add_f32 v[130:131], v[130:131], 1.0 op_sel_hi:[1,0]
	v_mul_f32_e32 v154, 0xbfb8aa3b, v154
	v_exp_f32_e32 v154, v154
	v_pk_mul_f32 v[130:131], v[130:131], v[134:135]
	v_pk_add_f32 v[154:155], v[154:155], 1.0 op_sel_hi:[1,0]
	v_pk_mul_f32 v[76:77], v[76:77], v[130:131]
	v_lshlrev_b32_e32 v131, 16, v132
	v_mul_f32_e32 v131, 0xbfb8aa3b, v131
	v_and_b32_e32 v132, 0xffff0000, v132
	v_exp_f32_e32 v131, v131
	v_mul_f32_e32 v132, 0xbfb8aa3b, v132
	v_exp_f32_e32 v132, v132
	v_pk_mul_f32 v[154:155], v[154:155], v[156:157]
	v_add_f32_e32 v131, 1.0, v131
	v_pk_mul_f32 v[74:75], v[74:75], v[154:155]
	v_lshlrev_b32_e32 v130, 16, v136
	v_rcp_f32_e32 v134, v131
	v_and_b32_e32 v131, 0xffff0000, v136
	v_add_f32_e32 v132, 1.0, v132
	v_lshlrev_b32_e32 v136, 16, v133
	v_and_b32_e32 v154, 0xffff0000, v133
	v_rcp_f32_e32 v135, v132
	v_lshlrev_b32_e32 v132, 16, v137
	v_mul_f32_e32 v136, 0xbfb8aa3b, v136
	v_and_b32_e32 v133, 0xffff0000, v137
	v_mul_f32_e32 v137, 0xbfb8aa3b, v154
	v_exp_f32_e32 v136, v136
	v_exp_f32_e32 v137, v137
	v_mul_f32_e32 v130, 0xbfb8aa3b, v130
	v_mul_f32_e32 v131, 0xbfb8aa3b, v131
	v_mul_f32_e32 v132, 0xbfb8aa3b, v132
	v_mul_f32_e32 v133, 0xbfb8aa3b, v133
	v_exp_f32_e32 v130, v130
	v_exp_f32_e32 v131, v131
	v_exp_f32_e32 v132, v132
	v_add_f32_e32 v136, 1.0, v136
	v_exp_f32_e32 v133, v133
	v_add_f32_e32 v137, 1.0, v137
	v_rcp_f32_e32 v136, v136
	v_rcp_f32_e32 v137, v137
	v_pk_add_f32 v[132:133], v[132:133], 1.0 op_sel_hi:[1,0]
	v_pk_add_f32 v[130:131], v[130:131], 1.0 op_sel_hi:[1,0]
	v_lshl_add_u64 v[154:155], v[152:153], 0, s[20:21]
	v_pk_mul_f32 v[130:131], v[130:131], v[134:135]
	v_pk_mul_f32 v[132:133], v[132:133], v[136:137]
	v_pk_mul_f32 v[78:79], v[78:79], v[130:131]
	v_pk_mul_f32 v[80:81], v[80:81], v[132:133]
	v_add_co_u32_e32 v130, vcc, s1, v152
	s_mov_b64 s[20:21], 0x90000
	s_nop 0
	v_addc_co_u32_e32 v131, vcc, 0, v153, vcc
	s_waitcnt vmcnt(10)
	s_nop 1
	v_mov_b32_e32 v130, v196
	v_mov_b32_e32 v131, v197
	v_mov_b32_e32 v132, v198
	v_mov_b32_e32 v133, v199
	s_nop 0
	v_mov_b32_e32 v134, v200
	v_mov_b32_e32 v135, v201
	v_mov_b32_e32 v136, v202
	v_mov_b32_e32 v137, v203
	global_load_dwordx4 v[196:199], v[250:251], off
	global_load_dwordx4 v[200:203], v[250:251], off offset:2048
	s_mov_b32 s1, 0xa0000
	v_lshlrev_b32_e32 v157, 16, v130
	v_mul_f32_e32 v157, 0xbfb8aa3b, v157
	v_and_b32_e32 v130, 0xffff0000, v130
	v_exp_f32_e32 v157, v157
	v_mul_f32_e32 v130, 0xbfb8aa3b, v130
	v_exp_f32_e32 v130, v130
	v_lshlrev_b32_e32 v156, 16, v134
	v_and_b32_e32 v134, 0xffff0000, v134
	v_add_f32_e32 v157, 1.0, v157
	v_mul_f32_e32 v134, 0xbfb8aa3b, v134
	v_rcp_f32_e32 v158, v157
	v_exp_f32_e32 v157, v134
	v_add_f32_e32 v130, 1.0, v130
	v_lshlrev_b32_e32 v134, 16, v131
	v_and_b32_e32 v160, 0xffff0000, v131
	v_rcp_f32_e32 v159, v130
	v_lshlrev_b32_e32 v130, 16, v135
	v_mul_f32_e32 v134, 0xbfb8aa3b, v134
	v_and_b32_e32 v131, 0xffff0000, v135
	v_mul_f32_e32 v135, 0xbfb8aa3b, v160
	v_exp_f32_e32 v134, v134
	v_exp_f32_e32 v135, v135
	v_mul_f32_e32 v130, 0xbfb8aa3b, v130
	v_mul_f32_e32 v131, 0xbfb8aa3b, v131
	v_exp_f32_e32 v130, v130
	v_add_f32_e32 v134, 1.0, v134
	v_exp_f32_e32 v131, v131
	v_add_f32_e32 v135, 1.0, v135
	v_rcp_f32_e32 v134, v134
	v_rcp_f32_e32 v135, v135
	v_mul_f32_e32 v156, 0xbfb8aa3b, v156
	v_exp_f32_e32 v156, v156
	v_pk_add_f32 v[130:131], v[130:131], 1.0 op_sel_hi:[1,0]
	v_pk_add_f32 v[156:157], v[156:157], 1.0 op_sel_hi:[1,0]
	v_pk_mul_f32 v[130:131], v[130:131], v[134:135]
	v_pk_mul_f32 v[156:157], v[156:157], v[158:159]
	v_pk_mul_f32 v[84:85], v[84:85], v[130:131]
	v_lshlrev_b32_e32 v131, 16, v136
	v_mul_f32_e32 v131, 0xbfb8aa3b, v131
	v_lshlrev_b32_e32 v130, 16, v132
	v_exp_f32_e32 v134, v131
	v_and_b32_e32 v131, 0xffff0000, v132
	v_and_b32_e32 v132, 0xffff0000, v136
	v_pk_mul_f32 v[82:83], v[82:83], v[156:157]
	v_mul_f32_e32 v132, 0xbfb8aa3b, v132
	v_lshlrev_b32_e32 v136, 16, v133
	v_and_b32_e32 v156, 0xffff0000, v133
	v_mul_f32_e32 v130, 0xbfb8aa3b, v130
	v_exp_f32_e32 v135, v132
	v_mul_f32_e32 v131, 0xbfb8aa3b, v131
	v_lshlrev_b32_e32 v132, 16, v137
	v_mul_f32_e32 v136, 0xbfb8aa3b, v136
	v_and_b32_e32 v133, 0xffff0000, v137
	v_mul_f32_e32 v137, 0xbfb8aa3b, v156
	v_exp_f32_e32 v130, v130
	v_exp_f32_e32 v131, v131
	v_exp_f32_e32 v136, v136
	v_exp_f32_e32 v137, v137
	v_mul_f32_e32 v132, 0xbfb8aa3b, v132
	v_mul_f32_e32 v133, 0xbfb8aa3b, v133
	v_add_f32_e32 v130, 1.0, v130
	v_add_f32_e32 v131, 1.0, v131
	v_exp_f32_e32 v132, v132
	v_add_f32_e32 v136, 1.0, v136
	v_exp_f32_e32 v133, v133
	v_add_f32_e32 v137, 1.0, v137
	v_rcp_f32_e32 v130, v130
	v_rcp_f32_e32 v131, v131
	v_rcp_f32_e32 v136, v136
	v_rcp_f32_e32 v137, v137
	v_pk_add_f32 v[132:133], v[132:133], 1.0 op_sel_hi:[1,0]
	v_pk_add_f32 v[134:135], v[134:135], 1.0 op_sel_hi:[1,0]
	v_pk_mul_f32 v[132:133], v[132:133], v[136:137]
	v_pk_mul_f32 v[130:131], v[134:135], v[130:131]
	v_pk_mul_f32 v[88:89], v[88:89], v[132:133]
	v_pk_mul_f32 v[86:87], v[86:87], v[130:131]
	s_nop 0
	s_waitcnt vmcnt(10)
; __device__ __forceinline__ float bflo(unsigned w) { return __uint_as_float(w << 16); }
; __device__ __forceinline__ float bfhi(unsigned w) { return __uint_as_float(w & 0xffff0000u); }
;     __device__ __forceinline__ void mid(f32x4 (&acc)[2][2][4][2], const Unit& u, int wr, int wc, int fr, int fq) const {
;         const int row0 = u.pm * BM + wr * 64 + fr, col0 = u.pn * BM + wc * 32 + 8 * fq;
; #pragma unroll
;         for (int ai = 0; ai < 2; ++ai)
; #pragma unroll
;             for (int m = 0; m < 4; ++m) { const bf16_t* gp = GL + (size_t)(row0 + ai * HALF + m * 16) * 2048 + col0;
; #pragma unroll
;                 for (int bj = 0; bj < 2; ++bj) { const u32x4 la = *(const u32x4*)(gp + bj * HALF), lb = *(const u32x4*)(gp + 1024 + bj * HALF);
; #pragma unroll
;                     for (int n = 0; n < 2; ++n)
; #pragma unroll
;                         for (int j = 0; j < 4; ++j) { const int e = n * 4 + j; const unsigned wa = la[e >> 1], wb = lb[e >> 1];
;                             const float a = (e & 1) ? bfhi(wa) : bflo(wa), b = (e & 1) ? bfhi(wb) : bflo(wb);
;                             acc[ai][bj][m][n][j] *= (1.0f + __expf(-b)) * __builtin_amdgcn_rcpf(1.0f + __expf(-a)); }
;                     asm volatile("" : "+v"(acc[ai][bj][m][0]), "+v"(acc[ai][bj][m][1]) :: "memory"); } }
	s_nop 1
	v_mov_b32_e32 v130, v204
	v_mov_b32_e32 v131, v205
	v_mov_b32_e32 v132, v206
	v_mov_b32_e32 v133, v207
	v_mov_b32_e32 v134, v208
	v_mov_b32_e32 v135, v209
	v_mov_b32_e32 v136, v210
	v_mov_b32_e32 v137, v211
	global_load_dwordx4 v[204:207], v[250:251], off offset:256
	global_load_dwordx4 v[208:211], v[250:251], off offset:2304
	v_lshlrev_b32_e32 v155, 16, v130
	v_mul_f32_e32 v155, 0xbfb8aa3b, v155
	v_and_b32_e32 v130, 0xffff0000, v130
	v_exp_f32_e32 v155, v155
	v_mul_f32_e32 v130, 0xbfb8aa3b, v130
	v_exp_f32_e32 v130, v130
	v_lshlrev_b32_e32 v154, 16, v134
	v_and_b32_e32 v134, 0xffff0000, v134
	v_add_f32_e32 v155, 1.0, v155
	v_mul_f32_e32 v134, 0xbfb8aa3b, v134
	v_rcp_f32_e32 v156, v155
	v_exp_f32_e32 v155, v134
	v_add_f32_e32 v130, 1.0, v130
	v_lshlrev_b32_e32 v134, 16, v131
	v_and_b32_e32 v158, 0xffff0000, v131
	v_rcp_f32_e32 v157, v130
	v_lshlrev_b32_e32 v130, 16, v135
	v_mul_f32_e32 v134, 0xbfb8aa3b, v134
	v_and_b32_e32 v131, 0xffff0000, v135
	v_mul_f32_e32 v135, 0xbfb8aa3b, v158
	v_exp_f32_e32 v134, v134
	v_exp_f32_e32 v135, v135
	v_mul_f32_e32 v130, 0xbfb8aa3b, v130
	v_mul_f32_e32 v131, 0xbfb8aa3b, v131
	v_exp_f32_e32 v130, v130
	v_add_f32_e32 v134, 1.0, v134
	v_exp_f32_e32 v131, v131
	v_add_f32_e32 v135, 1.0, v135
	v_rcp_f32_e32 v134, v134
	v_rcp_f32_e32 v135, v135
	v_pk_add_f32 v[130:131], v[130:131], 1.0 op_sel_hi:[1,0]
	v_mul_f32_e32 v154, 0xbfb8aa3b, v154
	v_exp_f32_e32 v154, v154
	v_pk_mul_f32 v[130:131], v[130:131], v[134:135]
	v_pk_add_f32 v[154:155], v[154:155], 1.0 op_sel_hi:[1,0]
	v_pk_mul_f32 v[92:93], v[92:93], v[130:131]
	v_lshlrev_b32_e32 v131, 16, v132
	v_mul_f32_e32 v131, 0xbfb8aa3b, v131
	v_and_b32_e32 v132, 0xffff0000, v132
	v_exp_f32_e32 v131, v131
	v_mul_f32_e32 v132, 0xbfb8aa3b, v132
	v_exp_f32_e32 v132, v132
	v_pk_mul_f32 v[154:155], v[154:155], v[156:157]
	v_add_f32_e32 v131, 1.0, v131
	v_pk_mul_f32 v[90:91], v[90:91], v[154:155]
	v_lshlrev_b32_e32 v130, 16, v136
	v_rcp_f32_e32 v134, v131
	v_and_b32_e32 v131, 0xffff0000, v136
	v_add_f32_e32 v132, 1.0, v132
	v_lshlrev_b32_e32 v136, 16, v133
	v_and_b32_e32 v154, 0xffff0000, v133
	v_rcp_f32_e32 v135, v132
	v_lshlrev_b32_e32 v132, 16, v137
	v_mul_f32_e32 v136, 0xbfb8aa3b, v136
	v_and_b32_e32 v133, 0xffff0000, v137
	v_mul_f32_e32 v137, 0xbfb8aa3b, v154
	v_exp_f32_e32 v136, v136
	v_exp_f32_e32 v137, v137
	v_mul_f32_e32 v130, 0xbfb8aa3b, v130
	v_mul_f32_e32 v131, 0xbfb8aa3b, v131
	v_mul_f32_e32 v132, 0xbfb8aa3b, v132
	v_mul_f32_e32 v133, 0xbfb8aa3b, v133
	v_exp_f32_e32 v130, v130
	v_exp_f32_e32 v131, v131
	v_exp_f32_e32 v132, v132
	v_add_f32_e32 v136, 1.0, v136
	v_exp_f32_e32 v133, v133
	v_add_f32_e32 v137, 1.0, v137
	v_rcp_f32_e32 v136, v136
	v_rcp_f32_e32 v137, v137
	v_pk_add_f32 v[132:133], v[132:133], 1.0 op_sel_hi:[1,0]
	v_pk_add_f32 v[130:131], v[130:131], 1.0 op_sel_hi:[1,0]
	v_lshl_add_u64 v[154:155], v[152:153], 0, s[20:21]
	v_pk_mul_f32 v[130:131], v[130:131], v[134:135]
	v_pk_mul_f32 v[132:133], v[132:133], v[136:137]
	v_pk_mul_f32 v[94:95], v[94:95], v[130:131]
	v_pk_mul_f32 v[96:97], v[96:97], v[132:133]
	v_add_co_u32_e32 v130, vcc, s94, v152
	s_mov_b64 s[20:21], 0xa0000
	s_nop 0
	v_addc_co_u32_e32 v131, vcc, 0, v153, vcc
	s_waitcnt vmcnt(10)
	s_nop 1
	v_mov_b32_e32 v130, v220
	v_mov_b32_e32 v131, v221
	v_mov_b32_e32 v132, v222
	v_mov_b32_e32 v133, v223
	s_nop 0
	v_mov_b32_e32 v134, v224
	v_mov_b32_e32 v135, v225
	v_mov_b32_e32 v136, v226
	v_mov_b32_e32 v137, v227
	v_lshlrev_b32_e32 v157, 16, v130
	v_mul_f32_e32 v157, 0xbfb8aa3b, v157
	v_and_b32_e32 v130, 0xffff0000, v130
	v_exp_f32_e32 v157, v157
	v_mul_f32_e32 v130, 0xbfb8aa3b, v130
	v_exp_f32_e32 v130, v130
	v_lshlrev_b32_e32 v156, 16, v134
	v_and_b32_e32 v134, 0xffff0000, v134
	v_add_f32_e32 v157, 1.0, v157
	v_mul_f32_e32 v134, 0xbfb8aa3b, v134
	v_rcp_f32_e32 v158, v157
	v_exp_f32_e32 v157, v134
	v_add_f32_e32 v130, 1.0, v130
	v_lshlrev_b32_e32 v134, 16, v131
	v_and_b32_e32 v160, 0xffff0000, v131
	v_rcp_f32_e32 v159, v130
	v_lshlrev_b32_e32 v130, 16, v135
	v_mul_f32_e32 v134, 0xbfb8aa3b, v134
	v_and_b32_e32 v131, 0xffff0000, v135
	v_mul_f32_e32 v135, 0xbfb8aa3b, v160
	v_exp_f32_e32 v134, v134
	v_exp_f32_e32 v135, v135
	v_mul_f32_e32 v130, 0xbfb8aa3b, v130
	v_mul_f32_e32 v131, 0xbfb8aa3b, v131
	v_exp_f32_e32 v130, v130
	v_add_f32_e32 v134, 1.0, v134
	v_exp_f32_e32 v131, v131
	v_add_f32_e32 v135, 1.0, v135
	v_rcp_f32_e32 v134, v134
	v_rcp_f32_e32 v135, v135
	v_mul_f32_e32 v156, 0xbfb8aa3b, v156
	v_exp_f32_e32 v156, v156
	v_pk_add_f32 v[130:131], v[130:131], 1.0 op_sel_hi:[1,0]
	v_pk_add_f32 v[156:157], v[156:157], 1.0 op_sel_hi:[1,0]
	v_pk_mul_f32 v[130:131], v[130:131], v[134:135]
	v_pk_mul_f32 v[156:157], v[156:157], v[158:159]
	v_pk_mul_f32 v[108:109], v[108:109], v[130:131]
	v_lshlrev_b32_e32 v131, 16, v136
	v_mul_f32_e32 v131, 0xbfb8aa3b, v131
	v_lshlrev_b32_e32 v130, 16, v132
	v_exp_f32_e32 v134, v131
	v_and_b32_e32 v131, 0xffff0000, v132
	v_and_b32_e32 v132, 0xffff0000, v136
	v_pk_mul_f32 v[106:107], v[106:107], v[156:157]
	v_mul_f32_e32 v132, 0xbfb8aa3b, v132
	v_lshlrev_b32_e32 v136, 16, v133
	v_and_b32_e32 v156, 0xffff0000, v133
	v_mul_f32_e32 v130, 0xbfb8aa3b, v130
	v_exp_f32_e32 v135, v132
	v_mul_f32_e32 v131, 0xbfb8aa3b, v131
	v_lshlrev_b32_e32 v132, 16, v137
	v_mul_f32_e32 v136, 0xbfb8aa3b, v136
	v_and_b32_e32 v133, 0xffff0000, v137
	v_mul_f32_e32 v137, 0xbfb8aa3b, v156
	v_exp_f32_e32 v130, v130
	v_exp_f32_e32 v131, v131
	v_exp_f32_e32 v136, v136
	v_exp_f32_e32 v137, v137
	v_mul_f32_e32 v132, 0xbfb8aa3b, v132
	v_mul_f32_e32 v133, 0xbfb8aa3b, v133
	v_add_f32_e32 v130, 1.0, v130
	v_add_f32_e32 v131, 1.0, v131
	v_exp_f32_e32 v132, v132
	v_add_f32_e32 v136, 1.0, v136
	v_exp_f32_e32 v133, v133
	v_add_f32_e32 v137, 1.0, v137
	v_rcp_f32_e32 v130, v130
	v_rcp_f32_e32 v131, v131
	v_rcp_f32_e32 v136, v136
	v_rcp_f32_e32 v137, v137
	v_pk_add_f32 v[132:133], v[132:133], 1.0 op_sel_hi:[1,0]
	v_pk_add_f32 v[134:135], v[134:135], 1.0 op_sel_hi:[1,0]
	v_pk_mul_f32 v[132:133], v[132:133], v[136:137]
	v_pk_mul_f32 v[130:131], v[134:135], v[130:131]
	v_pk_mul_f32 v[116:117], v[116:117], v[132:133]
	v_pk_mul_f32 v[114:115], v[114:115], v[130:131]
	s_nop 0
	s_waitcnt vmcnt(8)
; __device__ __forceinline__ float bflo(unsigned w) { return __uint_as_float(w << 16); }
; __device__ __forceinline__ float bfhi(unsigned w) { return __uint_as_float(w & 0xffff0000u); }
;     __device__ __forceinline__ void mid(f32x4 (&acc)[2][2][4][2], const Unit& u, int wr, int wc, int fr, int fq) const {
;         const int row0 = u.pm * BM + wr * 64 + fr, col0 = u.pn * BM + wc * 32 + 8 * fq;
; #pragma unroll
;         for (int ai = 0; ai < 2; ++ai)
; #pragma unroll
;             for (int m = 0; m < 4; ++m) { const bf16_t* gp = GL + (size_t)(row0 + ai * HALF + m * 16) * 2048 + col0;
; #pragma unroll
;                 for (int bj = 0; bj < 2; ++bj) { const u32x4 la = *(const u32x4*)(gp + bj * HALF), lb = *(const u32x4*)(gp + 1024 + bj * HALF);
; #pragma unroll
;                     for (int n = 0; n < 2; ++n)
; #pragma unroll
;                         for (int j = 0; j < 4; ++j) { const int e = n * 4 + j; const unsigned wa = la[e >> 1], wb = lb[e >> 1];
;                             const float a = (e & 1) ? bfhi(wa) : bflo(wa), b = (e & 1) ? bfhi(wb) : bflo(wb);
;                             acc[ai][bj][m][n][j] *= (1.0f + __expf(-b)) * __builtin_amdgcn_rcpf(1.0f + __expf(-a)); }
;                     asm volatile("" : "+v"(acc[ai][bj][m][0]), "+v"(acc[ai][bj][m][1]) :: "memory"); } }
	s_nop 1
	v_mov_b32_e32 v130, v228
	v_mov_b32_e32 v131, v229
	v_mov_b32_e32 v132, v230
	v_mov_b32_e32 v133, v231
	v_mov_b32_e32 v134, v232
	v_mov_b32_e32 v135, v233
	v_mov_b32_e32 v136, v234
	v_mov_b32_e32 v137, v235
	v_lshlrev_b32_e32 v155, 16, v130
	v_mul_f32_e32 v155, 0xbfb8aa3b, v155
	v_and_b32_e32 v130, 0xffff0000, v130
	v_exp_f32_e32 v155, v155
	v_mul_f32_e32 v130, 0xbfb8aa3b, v130
	v_exp_f32_e32 v130, v130
	v_lshlrev_b32_e32 v154, 16, v134
	v_and_b32_e32 v134, 0xffff0000, v134
	v_add_f32_e32 v155, 1.0, v155
	v_mul_f32_e32 v134, 0xbfb8aa3b, v134
	v_rcp_f32_e32 v156, v155
	v_exp_f32_e32 v155, v134
	v_add_f32_e32 v130, 1.0, v130
	v_lshlrev_b32_e32 v134, 16, v131
	v_and_b32_e32 v158, 0xffff0000, v131
	v_rcp_f32_e32 v157, v130
	v_lshlrev_b32_e32 v130, 16, v135
	v_mul_f32_e32 v134, 0xbfb8aa3b, v134
	v_and_b32_e32 v131, 0xffff0000, v135
	v_mul_f32_e32 v135, 0xbfb8aa3b, v158
	v_exp_f32_e32 v134, v134
	v_exp_f32_e32 v135, v135
	v_mul_f32_e32 v130, 0xbfb8aa3b, v130
	v_mul_f32_e32 v131, 0xbfb8aa3b, v131
	v_exp_f32_e32 v130, v130
	v_add_f32_e32 v134, 1.0, v134
	v_exp_f32_e32 v131, v131
	v_add_f32_e32 v135, 1.0, v135
	v_rcp_f32_e32 v134, v134
	v_rcp_f32_e32 v135, v135
	v_pk_add_f32 v[130:131], v[130:131], 1.0 op_sel_hi:[1,0]
	v_mul_f32_e32 v154, 0xbfb8aa3b, v154
	v_exp_f32_e32 v154, v154
	v_pk_mul_f32 v[130:131], v[130:131], v[134:135]
	v_pk_add_f32 v[154:155], v[154:155], 1.0 op_sel_hi:[1,0]
	v_pk_mul_f32 v[120:121], v[120:121], v[130:131]
	v_lshlrev_b32_e32 v131, 16, v132
	v_mul_f32_e32 v131, 0xbfb8aa3b, v131
	v_and_b32_e32 v132, 0xffff0000, v132
	v_exp_f32_e32 v131, v131
	v_mul_f32_e32 v132, 0xbfb8aa3b, v132
	v_exp_f32_e32 v132, v132
	v_pk_mul_f32 v[154:155], v[154:155], v[156:157]
	v_add_f32_e32 v131, 1.0, v131
	v_pk_mul_f32 v[118:119], v[118:119], v[154:155]
	v_lshlrev_b32_e32 v130, 16, v136
	v_rcp_f32_e32 v134, v131
	v_and_b32_e32 v131, 0xffff0000, v136
	v_add_f32_e32 v132, 1.0, v132
	v_lshlrev_b32_e32 v136, 16, v133
	v_and_b32_e32 v154, 0xffff0000, v133
	v_rcp_f32_e32 v135, v132
	v_lshlrev_b32_e32 v132, 16, v137
	v_mul_f32_e32 v136, 0xbfb8aa3b, v136
	v_and_b32_e32 v133, 0xffff0000, v137
	v_mul_f32_e32 v137, 0xbfb8aa3b, v154
	v_exp_f32_e32 v136, v136
	v_exp_f32_e32 v137, v137
	v_mul_f32_e32 v130, 0xbfb8aa3b, v130
	v_mul_f32_e32 v131, 0xbfb8aa3b, v131
	v_mul_f32_e32 v132, 0xbfb8aa3b, v132
	v_mul_f32_e32 v133, 0xbfb8aa3b, v133
	v_exp_f32_e32 v130, v130
	v_exp_f32_e32 v131, v131
	v_exp_f32_e32 v132, v132
	v_add_f32_e32 v136, 1.0, v136
	v_exp_f32_e32 v133, v133
	v_add_f32_e32 v137, 1.0, v137
	v_rcp_f32_e32 v136, v136
	v_rcp_f32_e32 v137, v137
	v_pk_add_f32 v[132:133], v[132:133], 1.0 op_sel_hi:[1,0]
	v_pk_add_f32 v[130:131], v[130:131], 1.0 op_sel_hi:[1,0]
	v_lshl_add_u64 v[154:155], v[152:153], 0, s[20:21]
	v_pk_mul_f32 v[130:131], v[130:131], v[134:135]
	v_pk_mul_f32 v[132:133], v[132:133], v[136:137]
	v_pk_mul_f32 v[122:123], v[122:123], v[130:131]
	v_pk_mul_f32 v[124:125], v[124:125], v[132:133]
	v_add_co_u32_e32 v130, vcc, s1, v152
	s_mov_b32 s1, 0xb0000
	s_nop 0
	v_addc_co_u32_e32 v131, vcc, 0, v153, vcc
	s_waitcnt vmcnt(6)
	s_nop 1
	v_mov_b32_e32 v130, v180
	v_mov_b32_e32 v131, v181
	v_mov_b32_e32 v132, v182
	v_mov_b32_e32 v133, v183
	s_nop 0
	v_mov_b32_e32 v134, v184
	v_mov_b32_e32 v135, v185
	v_mov_b32_e32 v136, v186
	v_mov_b32_e32 v137, v187
	s_mov_b64 s[20:21], 0xb0000
	v_lshlrev_b32_e32 v157, 16, v130
	v_mul_f32_e32 v157, 0xbfb8aa3b, v157
	v_and_b32_e32 v130, 0xffff0000, v130
	v_exp_f32_e32 v157, v157
	v_mul_f32_e32 v130, 0xbfb8aa3b, v130
	v_exp_f32_e32 v130, v130
	v_lshlrev_b32_e32 v156, 16, v134
	v_and_b32_e32 v134, 0xffff0000, v134
	v_add_f32_e32 v157, 1.0, v157
	v_mul_f32_e32 v134, 0xbfb8aa3b, v134
	v_rcp_f32_e32 v158, v157
	v_exp_f32_e32 v157, v134
	v_add_f32_e32 v130, 1.0, v130
	v_lshlrev_b32_e32 v134, 16, v131
	v_and_b32_e32 v160, 0xffff0000, v131
	v_rcp_f32_e32 v159, v130
	v_lshlrev_b32_e32 v130, 16, v135
	v_mul_f32_e32 v134, 0xbfb8aa3b, v134
	v_and_b32_e32 v131, 0xffff0000, v135
	v_mul_f32_e32 v135, 0xbfb8aa3b, v160
	v_exp_f32_e32 v134, v134
	v_exp_f32_e32 v135, v135
	v_mul_f32_e32 v130, 0xbfb8aa3b, v130
	v_mul_f32_e32 v131, 0xbfb8aa3b, v131
	v_exp_f32_e32 v130, v130
	v_add_f32_e32 v134, 1.0, v134
	v_exp_f32_e32 v131, v131
	v_add_f32_e32 v135, 1.0, v135
	v_rcp_f32_e32 v134, v134
	v_rcp_f32_e32 v135, v135
	v_mul_f32_e32 v156, 0xbfb8aa3b, v156
	v_exp_f32_e32 v156, v156
	v_pk_add_f32 v[130:131], v[130:131], 1.0 op_sel_hi:[1,0]
	v_pk_add_f32 v[156:157], v[156:157], 1.0 op_sel_hi:[1,0]
	v_pk_mul_f32 v[130:131], v[130:131], v[134:135]
	v_pk_mul_f32 v[156:157], v[156:157], v[158:159]
	v_pk_mul_f32 v[128:129], v[128:129], v[130:131]
	v_lshlrev_b32_e32 v131, 16, v136
	v_mul_f32_e32 v131, 0xbfb8aa3b, v131
	v_lshlrev_b32_e32 v130, 16, v132
	v_exp_f32_e32 v134, v131
	v_and_b32_e32 v131, 0xffff0000, v132
	v_and_b32_e32 v132, 0xffff0000, v136
	v_pk_mul_f32 v[126:127], v[126:127], v[156:157]
	v_mul_f32_e32 v132, 0xbfb8aa3b, v132
	v_lshlrev_b32_e32 v136, 16, v133
	v_and_b32_e32 v156, 0xffff0000, v133
	v_mul_f32_e32 v130, 0xbfb8aa3b, v130
	v_exp_f32_e32 v135, v132
	v_mul_f32_e32 v131, 0xbfb8aa3b, v131
	v_lshlrev_b32_e32 v132, 16, v137
	v_mul_f32_e32 v136, 0xbfb8aa3b, v136
	v_and_b32_e32 v133, 0xffff0000, v137
	v_mul_f32_e32 v137, 0xbfb8aa3b, v156
	v_exp_f32_e32 v130, v130
	v_exp_f32_e32 v131, v131
	v_exp_f32_e32 v136, v136
	v_exp_f32_e32 v137, v137
	v_mul_f32_e32 v132, 0xbfb8aa3b, v132
	v_mul_f32_e32 v133, 0xbfb8aa3b, v133
	v_add_f32_e32 v130, 1.0, v130
	v_add_f32_e32 v131, 1.0, v131
	v_exp_f32_e32 v132, v132
	v_add_f32_e32 v136, 1.0, v136
	v_exp_f32_e32 v133, v133
	v_add_f32_e32 v137, 1.0, v137
	v_rcp_f32_e32 v130, v130
	v_rcp_f32_e32 v131, v131
	v_rcp_f32_e32 v136, v136
	v_rcp_f32_e32 v137, v137
	v_pk_add_f32 v[132:133], v[132:133], 1.0 op_sel_hi:[1,0]
	v_pk_add_f32 v[134:135], v[134:135], 1.0 op_sel_hi:[1,0]
	v_pk_mul_f32 v[132:133], v[132:133], v[136:137]
	v_pk_mul_f32 v[130:131], v[134:135], v[130:131]
	v_pk_mul_f32 v[112:113], v[112:113], v[132:133]
	v_pk_mul_f32 v[110:111], v[110:111], v[130:131]
	s_nop 0
	s_waitcnt vmcnt(4)
; __device__ __forceinline__ float bflo(unsigned w) { return __uint_as_float(w << 16); }
; __device__ __forceinline__ float bfhi(unsigned w) { return __uint_as_float(w & 0xffff0000u); }
;     __device__ __forceinline__ void mid(f32x4 (&acc)[2][2][4][2], const Unit& u, int wr, int wc, int fr, int fq) const {
;         const int row0 = u.pm * BM + wr * 64 + fr, col0 = u.pn * BM + wc * 32 + 8 * fq;
; #pragma unroll
;         for (int ai = 0; ai < 2; ++ai)
; #pragma unroll
;             for (int m = 0; m < 4; ++m) { const bf16_t* gp = GL + (size_t)(row0 + ai * HALF + m * 16) * 2048 + col0;
; #pragma unroll
;                 for (int bj = 0; bj < 2; ++bj) { const u32x4 la = *(const u32x4*)(gp + bj * HALF), lb = *(const u32x4*)(gp + 1024 + bj * HALF);
; #pragma unroll
;                     for (int n = 0; n < 2; ++n)
; #pragma unroll
;                         for (int j = 0; j < 4; ++j) { const int e = n * 4 + j; const unsigned wa = la[e >> 1], wb = lb[e >> 1];
;                             const float a = (e & 1) ? bfhi(wa) : bflo(wa), b = (e & 1) ? bfhi(wb) : bflo(wb);
;                             acc[ai][bj][m][n][j] *= (1.0f + __expf(-b)) * __builtin_amdgcn_rcpf(1.0f + __expf(-a)); }
;                     asm volatile("" : "+v"(acc[ai][bj][m][0]), "+v"(acc[ai][bj][m][1]) :: "memory"); } }
	s_nop 1
	v_mov_b32_e32 v130, v188
	v_mov_b32_e32 v131, v189
	v_mov_b32_e32 v132, v190
	v_mov_b32_e32 v133, v191
	v_mov_b32_e32 v134, v192
	v_mov_b32_e32 v135, v193
	v_mov_b32_e32 v136, v194
	v_mov_b32_e32 v137, v195
	v_lshlrev_b32_e32 v155, 16, v130
	v_mul_f32_e32 v155, 0xbfb8aa3b, v155
	v_and_b32_e32 v130, 0xffff0000, v130
	v_exp_f32_e32 v155, v155
	v_mul_f32_e32 v130, 0xbfb8aa3b, v130
	v_exp_f32_e32 v130, v130
	v_lshlrev_b32_e32 v154, 16, v134
	v_and_b32_e32 v134, 0xffff0000, v134
	v_add_f32_e32 v155, 1.0, v155
	v_mul_f32_e32 v134, 0xbfb8aa3b, v134
	v_rcp_f32_e32 v156, v155
	v_exp_f32_e32 v155, v134
	v_add_f32_e32 v130, 1.0, v130
	v_lshlrev_b32_e32 v134, 16, v131
	v_and_b32_e32 v158, 0xffff0000, v131
	v_rcp_f32_e32 v157, v130
	v_lshlrev_b32_e32 v130, 16, v135
	v_mul_f32_e32 v134, 0xbfb8aa3b, v134
	v_and_b32_e32 v131, 0xffff0000, v135
	v_mul_f32_e32 v135, 0xbfb8aa3b, v158
	v_exp_f32_e32 v134, v134
	v_exp_f32_e32 v135, v135
	v_mul_f32_e32 v130, 0xbfb8aa3b, v130
	v_mul_f32_e32 v131, 0xbfb8aa3b, v131
	v_exp_f32_e32 v130, v130
	v_add_f32_e32 v134, 1.0, v134
	v_exp_f32_e32 v131, v131
	v_add_f32_e32 v135, 1.0, v135
	v_rcp_f32_e32 v134, v134
	v_rcp_f32_e32 v135, v135
	v_pk_add_f32 v[130:131], v[130:131], 1.0 op_sel_hi:[1,0]
	v_mul_f32_e32 v154, 0xbfb8aa3b, v154
	v_exp_f32_e32 v154, v154
	v_pk_mul_f32 v[130:131], v[130:131], v[134:135]
	v_pk_add_f32 v[154:155], v[154:155], 1.0 op_sel_hi:[1,0]
	v_pk_mul_f32 v[104:105], v[104:105], v[130:131]
	v_lshlrev_b32_e32 v131, 16, v132
	v_mul_f32_e32 v131, 0xbfb8aa3b, v131
	v_and_b32_e32 v132, 0xffff0000, v132
	v_exp_f32_e32 v131, v131
	v_mul_f32_e32 v132, 0xbfb8aa3b, v132
	v_exp_f32_e32 v132, v132
	v_pk_mul_f32 v[154:155], v[154:155], v[156:157]
	v_add_f32_e32 v131, 1.0, v131
	v_pk_mul_f32 v[102:103], v[102:103], v[154:155]
	v_lshlrev_b32_e32 v130, 16, v136
	v_rcp_f32_e32 v134, v131
	v_and_b32_e32 v131, 0xffff0000, v136
	v_add_f32_e32 v132, 1.0, v132
	v_lshlrev_b32_e32 v136, 16, v133
	v_and_b32_e32 v154, 0xffff0000, v133
	v_rcp_f32_e32 v135, v132
	v_lshlrev_b32_e32 v132, 16, v137
	v_mul_f32_e32 v136, 0xbfb8aa3b, v136
	v_and_b32_e32 v133, 0xffff0000, v137
	v_mul_f32_e32 v137, 0xbfb8aa3b, v154
	v_exp_f32_e32 v136, v136
	v_exp_f32_e32 v137, v137
	v_mul_f32_e32 v130, 0xbfb8aa3b, v130
	v_mul_f32_e32 v131, 0xbfb8aa3b, v131
	v_mul_f32_e32 v132, 0xbfb8aa3b, v132
	v_mul_f32_e32 v133, 0xbfb8aa3b, v133
	v_exp_f32_e32 v130, v130
	v_exp_f32_e32 v131, v131
	v_exp_f32_e32 v132, v132
	v_add_f32_e32 v136, 1.0, v136
	v_exp_f32_e32 v133, v133
	v_add_f32_e32 v137, 1.0, v137
	v_rcp_f32_e32 v136, v136
	v_rcp_f32_e32 v137, v137
	v_pk_add_f32 v[132:133], v[132:133], 1.0 op_sel_hi:[1,0]
	v_pk_add_f32 v[130:131], v[130:131], 1.0 op_sel_hi:[1,0]
	v_lshl_add_u64 v[154:155], v[152:153], 0, s[20:21]
	v_pk_mul_f32 v[130:131], v[130:131], v[134:135]
	v_pk_mul_f32 v[132:133], v[132:133], v[136:137]
	v_pk_mul_f32 v[98:99], v[98:99], v[130:131]
	v_pk_mul_f32 v[100:101], v[100:101], v[132:133]
	v_add_co_u32_e32 v130, vcc, s1, v152
	s_nop 1
	v_addc_co_u32_e32 v131, vcc, 0, v153, vcc
	s_waitcnt vmcnt(2)
; __device__ __forceinline__ float bflo(unsigned w) { return __uint_as_float(w << 16); }
; __device__ __forceinline__ float bfhi(unsigned w) { return __uint_as_float(w & 0xffff0000u); }
; #define PG8_BAR __builtin_amdgcn_s_barrier()
; template <bool CHAIN, class Epi, class Sched>
; __device__ __forceinline__ void gemm_phase(LAS unsigned char* lds, const int tid, const int K, const int lda, const int ldb, const Sched& S, const Epi& E) {
;     ...
;             if (wr == 0) PG8_BAR;
;             { PG8_EPI_IDS; E.mid(acc, cur, wr, wc, fr2, fq2); }
;             if (wr == 1) PG8_BAR;
;     __device__ __forceinline__ void mid(f32x4 (&acc)[2][2][4][2], const Unit& u, int wr, int wc, int fr, int fq) const {
;         const int row0 = u.pm * BM + wr * 64 + fr, col0 = u.pn * BM + wc * 32 + 8 * fq;
; #pragma unroll
;         for (int ai = 0; ai < 2; ++ai)
; #pragma unroll
;             for (int m = 0; m < 4; ++m) { const bf16_t* gp = GL + (size_t)(row0 + ai * HALF + m * 16) * 2048 + col0;
; #pragma unroll
;                 for (int bj = 0; bj < 2; ++bj) { const u32x4 la = *(const u32x4*)(gp + bj * HALF), lb = *(const u32x4*)(gp + 1024 + bj * HALF);
; #pragma unroll
;                     for (int n = 0; n < 2; ++n)
; #pragma unroll
;                         for (int j = 0; j < 4; ++j) { const int e = n * 4 + j; const unsigned wa = la[e >> 1], wb = lb[e >> 1];
;                             const float a = (e & 1) ? bfhi(wa) : bflo(wa), b = (e & 1) ? bfhi(wb) : bflo(wb);
;                             acc[ai][bj][m][n][j] *= (1.0f + __expf(-b)) * __builtin_amdgcn_rcpf(1.0f + __expf(-a)); }
;                     asm volatile("" : "+v"(acc[ai][bj][m][0]), "+v"(acc[ai][bj][m][1]) :: "memory"); } }
;     }
	s_nop 1
	v_mov_b32_e32 v130, v196
	v_mov_b32_e32 v131, v197
	v_mov_b32_e32 v132, v198
	v_mov_b32_e32 v133, v199
	s_nop 0
	v_mov_b32_e32 v134, v200
	v_mov_b32_e32 v135, v201
	v_mov_b32_e32 v136, v202
	v_mov_b32_e32 v137, v203
	s_andn2_b64 vcc, exec, s[54:55]
	v_lshlrev_b32_e32 v153, 16, v130
	v_mul_f32_e32 v153, 0xbfb8aa3b, v153
	v_and_b32_e32 v130, 0xffff0000, v130
	v_exp_f32_e32 v153, v153
	v_mul_f32_e32 v130, 0xbfb8aa3b, v130
	v_exp_f32_e32 v130, v130
	v_lshlrev_b32_e32 v152, 16, v134
	v_and_b32_e32 v134, 0xffff0000, v134
	v_add_f32_e32 v153, 1.0, v153
	v_mul_f32_e32 v134, 0xbfb8aa3b, v134
	v_rcp_f32_e32 v156, v153
	v_exp_f32_e32 v153, v134
	v_add_f32_e32 v130, 1.0, v130
	v_lshlrev_b32_e32 v134, 16, v131
	v_and_b32_e32 v158, 0xffff0000, v131
	v_rcp_f32_e32 v157, v130
	v_lshlrev_b32_e32 v130, 16, v135
	v_mul_f32_e32 v134, 0xbfb8aa3b, v134
	v_and_b32_e32 v131, 0xffff0000, v135
	v_mul_f32_e32 v135, 0xbfb8aa3b, v158
	v_exp_f32_e32 v134, v134
	v_exp_f32_e32 v135, v135
	v_mul_f32_e32 v130, 0xbfb8aa3b, v130
	v_mul_f32_e32 v131, 0xbfb8aa3b, v131
	v_exp_f32_e32 v130, v130
	v_add_f32_e32 v134, 1.0, v134
	v_exp_f32_e32 v131, v131
	v_add_f32_e32 v135, 1.0, v135
	v_rcp_f32_e32 v134, v134
	v_rcp_f32_e32 v135, v135
	v_mul_f32_e32 v152, 0xbfb8aa3b, v152
	v_exp_f32_e32 v152, v152
	v_pk_add_f32 v[130:131], v[130:131], 1.0 op_sel_hi:[1,0]
	v_pk_add_f32 v[152:153], v[152:153], 1.0 op_sel_hi:[1,0]
	v_pk_mul_f32 v[130:131], v[130:131], v[134:135]
	v_pk_mul_f32 v[152:153], v[152:153], v[156:157]
	v_pk_mul_f32 v[64:65], v[64:65], v[130:131]
	v_lshlrev_b32_e32 v131, 16, v136
	v_mul_f32_e32 v131, 0xbfb8aa3b, v131
	v_lshlrev_b32_e32 v130, 16, v132
	v_exp_f32_e32 v134, v131
	v_and_b32_e32 v131, 0xffff0000, v132
	v_and_b32_e32 v132, 0xffff0000, v136
	v_pk_mul_f32 v[62:63], v[62:63], v[152:153]
	v_mul_f32_e32 v132, 0xbfb8aa3b, v132
	v_lshlrev_b32_e32 v136, 16, v133
	v_and_b32_e32 v152, 0xffff0000, v133
	v_mul_f32_e32 v130, 0xbfb8aa3b, v130
	v_exp_f32_e32 v135, v132
	v_mul_f32_e32 v131, 0xbfb8aa3b, v131
	v_lshlrev_b32_e32 v132, 16, v137
	v_mul_f32_e32 v136, 0xbfb8aa3b, v136
	v_and_b32_e32 v133, 0xffff0000, v137
	v_mul_f32_e32 v137, 0xbfb8aa3b, v152
	v_exp_f32_e32 v130, v130
	v_exp_f32_e32 v131, v131
	v_exp_f32_e32 v136, v136
	v_exp_f32_e32 v137, v137
	v_mul_f32_e32 v132, 0xbfb8aa3b, v132
	v_mul_f32_e32 v133, 0xbfb8aa3b, v133
	v_add_f32_e32 v130, 1.0, v130
	v_add_f32_e32 v131, 1.0, v131
	v_exp_f32_e32 v132, v132
	v_add_f32_e32 v136, 1.0, v136
	v_exp_f32_e32 v133, v133
	v_add_f32_e32 v137, 1.0, v137
	v_rcp_f32_e32 v130, v130
	v_rcp_f32_e32 v131, v131
	v_rcp_f32_e32 v136, v136
	v_rcp_f32_e32 v137, v137
	v_pk_add_f32 v[132:133], v[132:133], 1.0 op_sel_hi:[1,0]
	v_pk_add_f32 v[134:135], v[134:135], 1.0 op_sel_hi:[1,0]
	v_pk_mul_f32 v[132:133], v[132:133], v[136:137]
	v_pk_mul_f32 v[130:131], v[134:135], v[130:131]
	v_pk_mul_f32 v[44:45], v[44:45], v[132:133]
	v_pk_mul_f32 v[42:43], v[42:43], v[130:131]
	s_nop 0
	s_waitcnt vmcnt(0)
	s_nop 1
	v_mov_b32_e32 v130, v204
	v_mov_b32_e32 v131, v205
	v_mov_b32_e32 v132, v206
	v_mov_b32_e32 v133, v207
	v_mov_b32_e32 v134, v208
	v_mov_b32_e32 v135, v209
	v_mov_b32_e32 v136, v210
	v_mov_b32_e32 v137, v211
	v_lshlrev_b32_e32 v153, 16, v130
	v_mul_f32_e32 v153, 0xbfb8aa3b, v153
	v_and_b32_e32 v130, 0xffff0000, v130
	v_exp_f32_e32 v153, v153
	v_mul_f32_e32 v130, 0xbfb8aa3b, v130
	v_exp_f32_e32 v130, v130
	v_lshlrev_b32_e32 v152, 16, v134
	v_and_b32_e32 v134, 0xffff0000, v134
	v_add_f32_e32 v153, 1.0, v153
	v_mul_f32_e32 v134, 0xbfb8aa3b, v134
	v_rcp_f32_e32 v154, v153
	v_exp_f32_e32 v153, v134
	v_add_f32_e32 v130, 1.0, v130
	v_lshlrev_b32_e32 v134, 16, v131
	v_and_b32_e32 v156, 0xffff0000, v131
	v_rcp_f32_e32 v155, v130
	v_lshlrev_b32_e32 v130, 16, v135
	v_mul_f32_e32 v134, 0xbfb8aa3b, v134
	v_and_b32_e32 v131, 0xffff0000, v135
	v_mul_f32_e32 v135, 0xbfb8aa3b, v156
	v_exp_f32_e32 v134, v134
	v_exp_f32_e32 v135, v135
	v_mul_f32_e32 v130, 0xbfb8aa3b, v130
	v_mul_f32_e32 v131, 0xbfb8aa3b, v131
	v_exp_f32_e32 v130, v130
	v_add_f32_e32 v134, 1.0, v134
	v_exp_f32_e32 v131, v131
	v_add_f32_e32 v135, 1.0, v135
	v_rcp_f32_e32 v134, v134
	v_rcp_f32_e32 v135, v135
	v_pk_add_f32 v[130:131], v[130:131], 1.0 op_sel_hi:[1,0]
	v_mul_f32_e32 v152, 0xbfb8aa3b, v152
	v_exp_f32_e32 v152, v152
	v_pk_mul_f32 v[130:131], v[130:131], v[134:135]
	v_pk_add_f32 v[152:153], v[152:153], 1.0 op_sel_hi:[1,0]
	v_pk_mul_f32 v[40:41], v[40:41], v[130:131]
	v_lshlrev_b32_e32 v131, 16, v132
	v_mul_f32_e32 v131, 0xbfb8aa3b, v131
	v_and_b32_e32 v132, 0xffff0000, v132
	v_exp_f32_e32 v131, v131
	v_mul_f32_e32 v132, 0xbfb8aa3b, v132
	v_exp_f32_e32 v132, v132
	v_pk_mul_f32 v[152:153], v[152:153], v[154:155]
	v_add_f32_e32 v131, 1.0, v131
	v_pk_mul_f32 v[38:39], v[38:39], v[152:153]
	v_lshlrev_b32_e32 v130, 16, v136
	v_rcp_f32_e32 v134, v131
	v_and_b32_e32 v131, 0xffff0000, v136
	v_add_f32_e32 v132, 1.0, v132
	v_lshlrev_b32_e32 v136, 16, v133
	v_and_b32_e32 v152, 0xffff0000, v133
	v_rcp_f32_e32 v135, v132
	v_lshlrev_b32_e32 v132, 16, v137
	v_mul_f32_e32 v136, 0xbfb8aa3b, v136
	v_and_b32_e32 v133, 0xffff0000, v137
	v_mul_f32_e32 v137, 0xbfb8aa3b, v152
	v_exp_f32_e32 v136, v136
	v_exp_f32_e32 v137, v137
	v_mul_f32_e32 v130, 0xbfb8aa3b, v130
	v_mul_f32_e32 v131, 0xbfb8aa3b, v131
	v_mul_f32_e32 v132, 0xbfb8aa3b, v132
	v_mul_f32_e32 v133, 0xbfb8aa3b, v133
	v_exp_f32_e32 v130, v130
	v_exp_f32_e32 v131, v131
	v_exp_f32_e32 v132, v132
	v_add_f32_e32 v136, 1.0, v136
	v_exp_f32_e32 v133, v133
	v_add_f32_e32 v137, 1.0, v137
	v_rcp_f32_e32 v136, v136
	v_rcp_f32_e32 v137, v137
	v_pk_add_f32 v[132:133], v[132:133], 1.0 op_sel_hi:[1,0]
	v_pk_add_f32 v[130:131], v[130:131], 1.0 op_sel_hi:[1,0]
	v_pk_mul_f32 v[132:133], v[132:133], v[136:137]
	v_pk_mul_f32 v[130:131], v[130:131], v[134:135]
	v_pk_mul_f32 v[36:37], v[36:37], v[132:133]
	v_pk_mul_f32 v[34:35], v[34:35], v[130:131]
	v_cndmask_b32_e64 v130, 0, 1, s[54:55]
	v_cmp_ne_u32_e64 s[42:43], 1, v130
	s_cbranch_vccnz .LBB0_386
	s_barrier

; __device__ __forceinline__ unsigned cvt_pk_bf16(float lo, float hi) { unsigned r; asm volatile("v_cvt_pk_bf16_f32 %0, %1, %2" : "=v"(r) : "v"(lo), "v"(hi)); return r; }
; __device__ __forceinline__ float bflo(unsigned w) { return __uint_as_float(w << 16); }
; __device__ __forceinline__ float bfhi(unsigned w) { return __uint_as_float(w & 0xffff0000u); }
;     __device__ __forceinline__ void operator()(const f32x4 (&acc)[2][2][4][2], const Unit& u, int wr, int wc, int fr, int fq) const {
;         const int row0 = u.pm * BM + wr * 64 + fr, col0 = u.pn * BM + wc * 32 + 8 * fq;
;         bf16_t* gout = u.slab < 0 ? G : SL + (size_t)u.slab * (1024 * 1024) - (size_t)ML * 1024;
; #pragma unroll
;         for (int ai = 0; ai < 2; ++ai)
; #pragma unroll
;             for (int m = 0; m < 4; ++m) { const size_t r = (size_t)(row0 + ai * HALF + m * 16);
; #pragma unroll
;                 for (int bj = 0; bj < 2; ++bj) { const u32x4 lb = *(const u32x4*)(GL + r * 2048 + 1024 + col0 + bj * HALF); float o[8];
; #pragma unroll
;                     for (int n = 0; n < 2; ++n)
; #pragma unroll
;                         for (int j = 0; j < 4; ++j) { const int e = n * 4 + j; const unsigned wb = lb[e >> 1]; const float b = (e & 1) ? bfhi(wb) : bflo(wb);
;                             o[e] = acc[ai][bj][m][n][j] * __builtin_amdgcn_rcpf(1.0f + __expf(-b)); }
;                     u32x4 w; w.x = cvt_pk_bf16(o[0], o[1]); w.y = cvt_pk_bf16(o[2], o[3]); w.z = cvt_pk_bf16(o[4], o[5]); w.w = cvt_pk_bf16(o[6], o[7]);
;                     *(u32x4*)(gout + r * 1024 + col0 + bj * HALF) = w; asm volatile("" ::: "memory"); } }
.LBB0_408:
	s_lshl_b64 s[0:1], s[8:9], 21
	v_readlane_b32 s22, v255, 26
	v_readlane_b32 s23, v255, 27
	s_add_u32 s0, s22, s0
	s_addc_u32 s1, s23, s1
	s_add_u32 s0, s0, 0xfe000000
	v_mov_b32_e32 v131, v167
	s_addc_u32 s1, s1, -1
	v_readlane_b32 s22, v255, 22
	s_cmp_lt_i32 s8, 0
	v_readlane_b32 s23, v255, 23
	s_cselect_b32 s1, s23, s1
	s_cselect_b32 s0, s22, s0
	v_ashrrev_i32_e32 v130, 1, v131
	s_lshl_b32 s22, s88, 8
	v_and_or_b32 v131, v131, 15, s4
	v_and_b32_e32 v130, -8, v130
	s_or_b32 s22, s22, s5
	v_lshl_add_u32 v134, s58, 8, v131
	v_add_u32_e32 v130, s22, v130
	v_ashrrev_i32_e32 v135, 31, v134
	v_ashrrev_i32_e32 v131, 31, v130
	v_lshlrev_b64 v[152:153], 12, v[134:135]
	v_lshlrev_b64 v[130:131], 1, v[130:131]
	v_lshl_add_u64 v[152:153], s[14:15], 0, v[152:153]
	v_lshl_add_u64 v[152:153], v[152:153], 0, v[130:131]
	v_mov_b32_e32 v178, v152
	v_mov_b32_e32 v179, v153
	v_add_co_u32_e32 v212, vcc, 0x10000, v152
	s_nop 1
	v_addc_co_u32_e32 v213, vcc, 0, v153, vcc
	v_add_co_u32_e32 v214, vcc, 0x20000, v152
	s_nop 1
	v_addc_co_u32_e32 v215, vcc, 0, v153, vcc
	v_add_co_u32_e32 v236, vcc, 0x30000, v152
	s_nop 1
	v_addc_co_u32_e32 v237, vcc, 0, v153, vcc
	v_add_co_u32_e32 v238, vcc, 0x80000, v152
	s_nop 1
	v_addc_co_u32_e32 v239, vcc, 0, v153, vcc
	v_add_co_u32_e32 v240, vcc, 0x90000, v152
	s_nop 1
	v_addc_co_u32_e32 v241, vcc, 0, v153, vcc
	v_add_co_u32_e32 v248, vcc, 0xa0000, v152
	s_nop 1
	v_addc_co_u32_e32 v249, vcc, 0, v153, vcc
	v_add_co_u32_e32 v250, vcc, 0xb0000, v152
	s_nop 1
	v_addc_co_u32_e32 v251, vcc, 0, v153, vcc
	global_load_dwordx4 v[180:183], v[178:179], off offset:2048
	global_load_dwordx4 v[184:187], v[178:179], off offset:2304
	global_load_dwordx4 v[188:191], v[212:213], off offset:2048
	global_load_dwordx4 v[192:195], v[212:213], off offset:2304
	global_load_dwordx4 v[196:199], v[214:215], off offset:2048
	global_load_dwordx4 v[200:203], v[214:215], off offset:2304
	global_load_dwordx4 v[204:207], v[236:237], off offset:2048
	global_load_dwordx4 v[208:211], v[236:237], off offset:2304
	s_waitcnt vmcnt(7)
	s_nop 1
	v_mov_b32_e32 v154, v180
	v_mov_b32_e32 v155, v181
	v_mov_b32_e32 v156, v182
	v_mov_b32_e32 v157, v183
	global_load_dwordx4 v[180:183], v[238:239], off offset:2048
	v_lshlrev_b64 v[136:137], 11, v[134:135]
	v_lshl_add_u64 v[132:133], s[0:1], 0, v[130:131]
	v_lshl_add_u64 v[136:137], v[132:133], 0, v[136:137]
	s_mov_b64 s[22:23], -1
	s_andn2_b64 vcc, exec, s[20:21]
	v_lshlrev_b32_e32 v135, 16, v154
	v_mul_f32_e32 v135, 0xbfb8aa3b, v135
	v_exp_f32_e32 v135, v135
	s_nop 0
	v_add_f32_e32 v135, 1.0, v135
	v_rcp_f32_e32 v135, v135
	s_nop 0
	v_mul_f32_e32 v0, v0, v135
	v_and_b32_e32 v135, 0xffff0000, v154
	v_mul_f32_e32 v135, 0xbfb8aa3b, v135
	v_exp_f32_e32 v135, v135
	s_nop 0
	v_add_f32_e32 v135, 1.0, v135
	v_rcp_f32_e32 v135, v135
	s_nop 0
	v_mul_f32_e32 v1, v1, v135
	v_lshlrev_b32_e32 v135, 16, v155
	v_mul_f32_e32 v135, 0xbfb8aa3b, v135
	v_exp_f32_e32 v135, v135
	v_cvt_pk_bf16_f32 v0, v0, v1
	s_nop 0
	v_add_f32_e32 v135, 1.0, v135
	v_rcp_f32_e32 v135, v135
	s_nop 0
	v_mul_f32_e32 v2, v2, v135
	v_and_b32_e32 v135, 0xffff0000, v155
	v_mul_f32_e32 v135, 0xbfb8aa3b, v135
	v_exp_f32_e32 v135, v135
	s_nop 0
	v_add_f32_e32 v135, 1.0, v135
	v_rcp_f32_e32 v135, v135
	s_nop 0
	v_mul_f32_e32 v3, v3, v135
	v_lshlrev_b32_e32 v135, 16, v156
	v_mul_f32_e32 v135, 0xbfb8aa3b, v135
	v_exp_f32_e32 v135, v135
	v_cvt_pk_bf16_f32 v1, v2, v3
	s_nop 0
	v_add_f32_e32 v135, 1.0, v135
	v_rcp_f32_e32 v135, v135
	s_nop 0
	v_mul_f32_e32 v4, v4, v135
	v_and_b32_e32 v135, 0xffff0000, v156
	v_mul_f32_e32 v135, 0xbfb8aa3b, v135
	v_exp_f32_e32 v135, v135
	s_nop 0
	v_add_f32_e32 v135, 1.0, v135
	v_rcp_f32_e32 v135, v135
	s_nop 0
	v_mul_f32_e32 v5, v5, v135
	v_lshlrev_b32_e32 v135, 16, v157
	v_mul_f32_e32 v135, 0xbfb8aa3b, v135
	v_exp_f32_e32 v135, v135
	v_cvt_pk_bf16_f32 v2, v4, v5
	s_nop 0
	v_add_f32_e32 v135, 1.0, v135
	v_rcp_f32_e32 v135, v135
	s_nop 0
	v_mul_f32_e32 v6, v6, v135
	v_and_b32_e32 v135, 0xffff0000, v157
	v_mul_f32_e32 v135, 0xbfb8aa3b, v135
	v_exp_f32_e32 v135, v135
	s_nop 0
	v_add_f32_e32 v135, 1.0, v135
	v_rcp_f32_e32 v135, v135
	s_nop 0
	v_mul_f32_e32 v7, v7, v135
	v_cvt_pk_bf16_f32 v3, v6, v7
	global_store_dwordx4 v[136:137], v[0:3], off sc1
	s_waitcnt vmcnt(8)
	s_nop 1
	v_mov_b32_e32 v0, v184
	v_mov_b32_e32 v1, v185
	v_mov_b32_e32 v2, v186
	v_mov_b32_e32 v3, v187
	global_load_dwordx4 v[184:187], v[238:239], off offset:2304
	v_lshlrev_b32_e32 v4, 16, v0
	v_and_b32_e32 v0, 0xffff0000, v0
	v_mul_f32_e32 v0, 0xbfb8aa3b, v0
	v_lshlrev_b32_e32 v5, 16, v1
	v_and_b32_e32 v1, 0xffff0000, v1
	v_lshlrev_b32_e32 v6, 16, v2
	v_and_b32_e32 v2, 0xffff0000, v2
	v_lshlrev_b32_e32 v7, 16, v3
	v_and_b32_e32 v3, 0xffff0000, v3
	v_mul_f32_e32 v4, 0xbfb8aa3b, v4
	v_exp_f32_e32 v0, v0
	v_mul_f32_e32 v1, 0xbfb8aa3b, v1
	v_mul_f32_e32 v2, 0xbfb8aa3b, v2
	v_mul_f32_e32 v3, 0xbfb8aa3b, v3
	v_exp_f32_e32 v4, v4
	v_mul_f32_e32 v5, 0xbfb8aa3b, v5
	v_exp_f32_e32 v1, v1
	v_mul_f32_e32 v6, 0xbfb8aa3b, v6
	v_exp_f32_e32 v2, v2
	v_mul_f32_e32 v7, 0xbfb8aa3b, v7
	v_exp_f32_e32 v3, v3
	v_exp_f32_e32 v5, v5
	v_exp_f32_e32 v6, v6
	v_exp_f32_e32 v7, v7
	v_add_f32_e32 v0, 1.0, v0
	v_add_f32_e32 v4, 1.0, v4
	v_rcp_f32_e32 v0, v0
	v_add_f32_e32 v1, 1.0, v1
	v_add_f32_e32 v2, 1.0, v2
	v_add_f32_e32 v3, 1.0, v3
	v_rcp_f32_e32 v4, v4
	v_add_f32_e32 v5, 1.0, v5
	v_rcp_f32_e32 v1, v1
	v_add_f32_e32 v6, 1.0, v6
	v_rcp_f32_e32 v2, v2
	v_add_f32_e32 v7, 1.0, v7
	v_rcp_f32_e32 v3, v3
	v_rcp_f32_e32 v5, v5
	v_rcp_f32_e32 v6, v6
	v_rcp_f32_e32 v7, v7
	v_mul_f32_e32 v0, v9, v0
	v_mul_f32_e32 v4, v8, v4
	v_mul_f32_e32 v1, v11, v1
	v_mul_f32_e32 v2, v13, v2
	v_mul_f32_e32 v3, v15, v3
	v_cvt_pk_bf16_f32 v0, v4, v0
	v_mul_f32_e32 v5, v10, v5
	v_mul_f32_e32 v6, v12, v6
	v_mul_f32_e32 v7, v14, v7
	v_cvt_pk_bf16_f32 v1, v5, v1
	v_cvt_pk_bf16_f32 v2, v6, v2
	v_cvt_pk_bf16_f32 v3, v7, v3
	global_store_dwordx4 v[136:137], v[0:3], off offset:256 sc1
	s_nop 1
	v_or_b32_e32 v0, 16, v134
	v_ashrrev_i32_e32 v1, 31, v0
	v_lshlrev_b64 v[2:3], 12, v[0:1]
	v_lshl_add_u64 v[2:3], s[14:15], 0, v[2:3]
	v_lshl_add_u64 v[2:3], v[2:3], 0, v[130:131]
	s_waitcnt vmcnt(9)
; __device__ __forceinline__ unsigned cvt_pk_bf16(float lo, float hi) { unsigned r; asm volatile("v_cvt_pk_bf16_f32 %0, %1, %2" : "=v"(r) : "v"(lo), "v"(hi)); return r; }
; __device__ __forceinline__ float bflo(unsigned w) { return __uint_as_float(w << 16); }
; __device__ __forceinline__ float bfhi(unsigned w) { return __uint_as_float(w & 0xffff0000u); }
;     __device__ __forceinline__ void operator()(const f32x4 (&acc)[2][2][4][2], const Unit& u, int wr, int wc, int fr, int fq) const {
;     ...
;             for (int m = 0; m < 4; ++m) { const size_t r = (size_t)(row0 + ai * HALF + m * 16);
; #pragma unroll
;                 for (int bj = 0; bj < 2; ++bj) { const u32x4 lb = *(const u32x4*)(GL + r * 2048 + 1024 + col0 + bj * HALF); float o[8];
; #pragma unroll
;                     for (int n = 0; n < 2; ++n)
; #pragma unroll
;                         for (int j = 0; j < 4; ++j) { const int e = n * 4 + j; const unsigned wb = lb[e >> 1]; const float b = (e & 1) ? bfhi(wb) : bflo(wb);
;                             o[e] = acc[ai][bj][m][n][j] * __builtin_amdgcn_rcpf(1.0f + __expf(-b)); }
;                     u32x4 w; w.x = cvt_pk_bf16(o[0], o[1]); w.y = cvt_pk_bf16(o[2], o[3]); w.z = cvt_pk_bf16(o[4], o[5]); w.w = cvt_pk_bf16(o[6], o[7]);
;                     *(u32x4*)(gout + r * 1024 + col0 + bj * HALF) = w; asm volatile("" ::: "memory"); } }
	s_nop 1
	v_mov_b32_e32 v4, v188
	v_mov_b32_e32 v5, v189
	v_mov_b32_e32 v6, v190
	v_mov_b32_e32 v7, v191
	global_load_dwordx4 v[188:191], v[240:241], off offset:2048
	v_lshlrev_b64 v[0:1], 11, v[0:1]
	v_lshl_add_u64 v[0:1], v[132:133], 0, v[0:1]
	v_lshlrev_b32_e32 v8, 16, v4
	v_and_b32_e32 v4, 0xffff0000, v4
	v_lshlrev_b32_e32 v9, 16, v5
	v_and_b32_e32 v5, 0xffff0000, v5
	v_lshlrev_b32_e32 v10, 16, v6
	v_and_b32_e32 v6, 0xffff0000, v6
	v_lshlrev_b32_e32 v11, 16, v7
	v_and_b32_e32 v7, 0xffff0000, v7
	v_mul_f32_e32 v4, 0xbfb8aa3b, v4
	v_mul_f32_e32 v5, 0xbfb8aa3b, v5
	v_mul_f32_e32 v6, 0xbfb8aa3b, v6
	v_mul_f32_e32 v7, 0xbfb8aa3b, v7
	v_mul_f32_e32 v8, 0xbfb8aa3b, v8
	v_exp_f32_e32 v4, v4
	v_mul_f32_e32 v9, 0xbfb8aa3b, v9
	v_exp_f32_e32 v5, v5
	v_mul_f32_e32 v10, 0xbfb8aa3b, v10
	v_exp_f32_e32 v6, v6
	v_mul_f32_e32 v11, 0xbfb8aa3b, v11
	v_exp_f32_e32 v7, v7
	v_exp_f32_e32 v8, v8
	v_exp_f32_e32 v9, v9
	v_exp_f32_e32 v10, v10
	v_exp_f32_e32 v11, v11
	v_add_f32_e32 v4, 1.0, v4
	v_add_f32_e32 v5, 1.0, v5
	v_add_f32_e32 v6, 1.0, v6
	v_add_f32_e32 v7, 1.0, v7
	v_add_f32_e32 v8, 1.0, v8
	v_rcp_f32_e32 v4, v4
	v_add_f32_e32 v9, 1.0, v9
	v_rcp_f32_e32 v5, v5
	v_add_f32_e32 v10, 1.0, v10
	v_rcp_f32_e32 v6, v6
	v_add_f32_e32 v11, 1.0, v11
	v_rcp_f32_e32 v7, v7
	v_rcp_f32_e32 v8, v8
	v_rcp_f32_e32 v9, v9
	v_rcp_f32_e32 v10, v10
	v_rcp_f32_e32 v11, v11
	v_mul_f32_e32 v4, v17, v4
	v_mul_f32_e32 v5, v19, v5
	v_mul_f32_e32 v6, v21, v6
	v_mul_f32_e32 v7, v23, v7
	v_mul_f32_e32 v8, v16, v8
	v_mul_f32_e32 v9, v18, v9
	v_mul_f32_e32 v10, v20, v10
	v_mul_f32_e32 v11, v22, v11
	v_cvt_pk_bf16_f32 v4, v8, v4
	v_cvt_pk_bf16_f32 v5, v9, v5
	v_cvt_pk_bf16_f32 v6, v10, v6
	v_cvt_pk_bf16_f32 v7, v11, v7
	global_store_dwordx4 v[0:1], v[4:7], off sc1
	s_waitcnt vmcnt(10)
	s_nop 1
	v_mov_b32_e32 v2, v192
	v_mov_b32_e32 v3, v193
	v_mov_b32_e32 v4, v194
	v_mov_b32_e32 v5, v195
	global_load_dwordx4 v[192:195], v[240:241], off offset:2304
	v_lshlrev_b32_e32 v8, 16, v4
	v_lshlrev_b32_e32 v6, 16, v2
	v_and_b32_e32 v2, 0xffff0000, v2
	v_lshlrev_b32_e32 v7, 16, v3
	v_and_b32_e32 v3, 0xffff0000, v3
	v_and_b32_e32 v4, 0xffff0000, v4
	v_lshlrev_b32_e32 v9, 16, v5
	v_and_b32_e32 v5, 0xffff0000, v5
	v_mul_f32_e32 v2, 0xbfb8aa3b, v2
	v_mul_f32_e32 v3, 0xbfb8aa3b, v3
	v_mul_f32_e32 v4, 0xbfb8aa3b, v4
	v_mul_f32_e32 v5, 0xbfb8aa3b, v5
	v_mul_f32_e32 v6, 0xbfb8aa3b, v6
	v_exp_f32_e32 v2, v2
	v_mul_f32_e32 v7, 0xbfb8aa3b, v7
	v_exp_f32_e32 v3, v3
	v_mul_f32_e32 v8, 0xbfb8aa3b, v8
	v_exp_f32_e32 v4, v4
	v_mul_f32_e32 v9, 0xbfb8aa3b, v9
	v_exp_f32_e32 v5, v5
	v_exp_f32_e32 v6, v6
	v_exp_f32_e32 v7, v7
	v_exp_f32_e32 v8, v8
	v_exp_f32_e32 v9, v9
	v_add_f32_e32 v2, 1.0, v2
	v_add_f32_e32 v3, 1.0, v3
	v_add_f32_e32 v4, 1.0, v4
	v_add_f32_e32 v5, 1.0, v5
	v_add_f32_e32 v6, 1.0, v6
	v_rcp_f32_e32 v2, v2
	v_add_f32_e32 v7, 1.0, v7
	v_rcp_f32_e32 v3, v3
	v_add_f32_e32 v8, 1.0, v8
	v_rcp_f32_e32 v4, v4
	v_add_f32_e32 v9, 1.0, v9
	v_rcp_f32_e32 v5, v5
	v_rcp_f32_e32 v6, v6
	v_rcp_f32_e32 v7, v7
	v_rcp_f32_e32 v8, v8
	v_rcp_f32_e32 v9, v9
	v_mul_f32_e32 v2, v25, v2
	v_mul_f32_e32 v3, v27, v3
	v_mul_f32_e32 v4, v29, v4
	v_mul_f32_e32 v5, v31, v5
	v_mul_f32_e32 v6, v24, v6
	v_mul_f32_e32 v7, v26, v7
	v_mul_f32_e32 v8, v28, v8
	v_mul_f32_e32 v9, v30, v9
	v_cvt_pk_bf16_f32 v2, v6, v2
	v_cvt_pk_bf16_f32 v3, v7, v3
	v_cvt_pk_bf16_f32 v4, v8, v4
	v_cvt_pk_bf16_f32 v5, v9, v5
	global_store_dwordx4 v[0:1], v[2:5], off offset:256 sc1
	v_or_b32_e32 v0, 32, v134
	v_ashrrev_i32_e32 v1, 31, v0
	v_lshlrev_b64 v[2:3], 12, v[0:1]
	v_lshl_add_u64 v[2:3], s[14:15], 0, v[2:3]
	v_lshl_add_u64 v[2:3], v[2:3], 0, v[130:131]
	s_waitcnt vmcnt(11)
	s_nop 1
	v_mov_b32_e32 v4, v196
	v_mov_b32_e32 v5, v197
	v_mov_b32_e32 v6, v198
	v_mov_b32_e32 v7, v199
	global_load_dwordx4 v[196:199], v[248:249], off offset:2048
	v_lshlrev_b64 v[0:1], 11, v[0:1]
	v_lshl_add_u64 v[0:1], v[132:133], 0, v[0:1]
	v_lshlrev_b32_e32 v8, 16, v4
	v_and_b32_e32 v4, 0xffff0000, v4
	v_lshlrev_b32_e32 v9, 16, v5
	v_and_b32_e32 v5, 0xffff0000, v5
	v_lshlrev_b32_e32 v10, 16, v6
	v_and_b32_e32 v6, 0xffff0000, v6
	v_lshlrev_b32_e32 v11, 16, v7
	v_and_b32_e32 v7, 0xffff0000, v7
	v_mul_f32_e32 v4, 0xbfb8aa3b, v4
	v_mul_f32_e32 v5, 0xbfb8aa3b, v5
	v_mul_f32_e32 v6, 0xbfb8aa3b, v6
	v_mul_f32_e32 v7, 0xbfb8aa3b, v7
	v_mul_f32_e32 v8, 0xbfb8aa3b, v8
	v_exp_f32_e32 v4, v4
	v_mul_f32_e32 v9, 0xbfb8aa3b, v9
	v_exp_f32_e32 v5, v5
	v_mul_f32_e32 v10, 0xbfb8aa3b, v10
	v_exp_f32_e32 v6, v6
	v_mul_f32_e32 v11, 0xbfb8aa3b, v11
	v_exp_f32_e32 v7, v7
	v_exp_f32_e32 v8, v8
	v_exp_f32_e32 v9, v9
	v_exp_f32_e32 v10, v10
	v_exp_f32_e32 v11, v11
	v_add_f32_e32 v4, 1.0, v4
	v_add_f32_e32 v5, 1.0, v5
	v_add_f32_e32 v6, 1.0, v6
	v_add_f32_e32 v7, 1.0, v7
	v_add_f32_e32 v8, 1.0, v8
	v_rcp_f32_e32 v4, v4
	v_add_f32_e32 v9, 1.0, v9
	v_rcp_f32_e32 v5, v5
	v_add_f32_e32 v10, 1.0, v10
	v_rcp_f32_e32 v6, v6
	v_add_f32_e32 v11, 1.0, v11
	v_rcp_f32_e32 v7, v7
	v_rcp_f32_e32 v8, v8
	v_rcp_f32_e32 v9, v9
	v_rcp_f32_e32 v10, v10
	v_rcp_f32_e32 v11, v11
	v_mul_f32_e32 v4, v47, v4
	v_mul_f32_e32 v5, v49, v5
	v_mul_f32_e32 v6, v51, v6
	v_mul_f32_e32 v7, v53, v7
	v_mul_f32_e32 v8, v46, v8
	v_mul_f32_e32 v9, v48, v9
	v_mul_f32_e32 v10, v50, v10
	v_mul_f32_e32 v11, v52, v11
	v_cvt_pk_bf16_f32 v4, v8, v4
	v_cvt_pk_bf16_f32 v5, v9, v5
	v_cvt_pk_bf16_f32 v6, v10, v6
	v_cvt_pk_bf16_f32 v7, v11, v7
	global_store_dwordx4 v[0:1], v[4:7], off sc1
	s_waitcnt vmcnt(12)
; __device__ __forceinline__ unsigned cvt_pk_bf16(float lo, float hi) { unsigned r; asm volatile("v_cvt_pk_bf16_f32 %0, %1, %2" : "=v"(r) : "v"(lo), "v"(hi)); return r; }
; __device__ __forceinline__ float bflo(unsigned w) { return __uint_as_float(w << 16); }
; __device__ __forceinline__ float bfhi(unsigned w) { return __uint_as_float(w & 0xffff0000u); }
;     __device__ __forceinline__ void operator()(const f32x4 (&acc)[2][2][4][2], const Unit& u, int wr, int wc, int fr, int fq) const {
;     ...
;             for (int m = 0; m < 4; ++m) { const size_t r = (size_t)(row0 + ai * HALF + m * 16);
; #pragma unroll
;                 for (int bj = 0; bj < 2; ++bj) { const u32x4 lb = *(const u32x4*)(GL + r * 2048 + 1024 + col0 + bj * HALF); float o[8];
; #pragma unroll
;                     for (int n = 0; n < 2; ++n)
; #pragma unroll
;                         for (int j = 0; j < 4; ++j) { const int e = n * 4 + j; const unsigned wb = lb[e >> 1]; const float b = (e & 1) ? bfhi(wb) : bflo(wb);
;                             o[e] = acc[ai][bj][m][n][j] * __builtin_amdgcn_rcpf(1.0f + __expf(-b)); }
;                     u32x4 w; w.x = cvt_pk_bf16(o[0], o[1]); w.y = cvt_pk_bf16(o[2], o[3]); w.z = cvt_pk_bf16(o[4], o[5]); w.w = cvt_pk_bf16(o[6], o[7]);
;                     *(u32x4*)(gout + r * 1024 + col0 + bj * HALF) = w; asm volatile("" ::: "memory"); } }
	s_nop 1
	v_mov_b32_e32 v2, v200
	v_mov_b32_e32 v3, v201
	v_mov_b32_e32 v4, v202
	v_mov_b32_e32 v5, v203
	global_load_dwordx4 v[200:203], v[248:249], off offset:2304
	v_lshlrev_b32_e32 v8, 16, v4
	v_lshlrev_b32_e32 v6, 16, v2
	v_and_b32_e32 v2, 0xffff0000, v2
	v_lshlrev_b32_e32 v7, 16, v3
	v_and_b32_e32 v3, 0xffff0000, v3
	v_and_b32_e32 v4, 0xffff0000, v4
	v_lshlrev_b32_e32 v9, 16, v5
	v_and_b32_e32 v5, 0xffff0000, v5
	v_mul_f32_e32 v2, 0xbfb8aa3b, v2
	v_mul_f32_e32 v3, 0xbfb8aa3b, v3
	v_mul_f32_e32 v4, 0xbfb8aa3b, v4
	v_mul_f32_e32 v5, 0xbfb8aa3b, v5
	v_mul_f32_e32 v6, 0xbfb8aa3b, v6
	v_exp_f32_e32 v2, v2
	v_mul_f32_e32 v7, 0xbfb8aa3b, v7
	v_exp_f32_e32 v3, v3
	v_mul_f32_e32 v8, 0xbfb8aa3b, v8
	v_exp_f32_e32 v4, v4
	v_mul_f32_e32 v9, 0xbfb8aa3b, v9
	v_exp_f32_e32 v5, v5
	v_exp_f32_e32 v6, v6
	v_exp_f32_e32 v7, v7
	v_exp_f32_e32 v8, v8
	v_exp_f32_e32 v9, v9
	v_add_f32_e32 v2, 1.0, v2
	v_add_f32_e32 v3, 1.0, v3
	v_add_f32_e32 v4, 1.0, v4
	v_add_f32_e32 v5, 1.0, v5
	v_add_f32_e32 v6, 1.0, v6
	v_rcp_f32_e32 v2, v2
	v_add_f32_e32 v7, 1.0, v7
	v_rcp_f32_e32 v3, v3
	v_add_f32_e32 v8, 1.0, v8
	v_rcp_f32_e32 v4, v4
	v_add_f32_e32 v9, 1.0, v9
	v_rcp_f32_e32 v5, v5
	v_rcp_f32_e32 v6, v6
	v_rcp_f32_e32 v7, v7
	v_rcp_f32_e32 v8, v8
	v_rcp_f32_e32 v9, v9
	v_mul_f32_e32 v2, v55, v2
	v_mul_f32_e32 v3, v57, v3
	v_mul_f32_e32 v4, v59, v4
	v_mul_f32_e32 v5, v61, v5
	v_mul_f32_e32 v6, v54, v6
	v_mul_f32_e32 v7, v56, v7
	v_mul_f32_e32 v8, v58, v8
	v_mul_f32_e32 v9, v60, v9
	v_cvt_pk_bf16_f32 v2, v6, v2
	v_cvt_pk_bf16_f32 v3, v7, v3
	v_cvt_pk_bf16_f32 v4, v8, v4
	v_cvt_pk_bf16_f32 v5, v9, v5
	global_store_dwordx4 v[0:1], v[2:5], off offset:256 sc1
	v_or_b32_e32 v0, 48, v134
	v_ashrrev_i32_e32 v1, 31, v0
	v_lshlrev_b64 v[2:3], 12, v[0:1]
	v_lshl_add_u64 v[2:3], s[14:15], 0, v[2:3]
	v_lshl_add_u64 v[2:3], v[2:3], 0, v[130:131]
	s_waitcnt vmcnt(13)
	s_nop 1
	v_mov_b32_e32 v4, v204
	v_mov_b32_e32 v5, v205
	v_mov_b32_e32 v6, v206
	v_mov_b32_e32 v7, v207
	global_load_dwordx4 v[204:207], v[250:251], off offset:2048
	v_lshlrev_b64 v[0:1], 11, v[0:1]
	v_lshl_add_u64 v[0:1], v[132:133], 0, v[0:1]
	v_lshlrev_b32_e32 v8, 16, v4
	v_and_b32_e32 v4, 0xffff0000, v4
	v_lshlrev_b32_e32 v9, 16, v5
	v_and_b32_e32 v5, 0xffff0000, v5
	v_lshlrev_b32_e32 v10, 16, v6
	v_and_b32_e32 v6, 0xffff0000, v6
	v_lshlrev_b32_e32 v11, 16, v7
	v_and_b32_e32 v7, 0xffff0000, v7
	v_mul_f32_e32 v4, 0xbfb8aa3b, v4
	v_mul_f32_e32 v5, 0xbfb8aa3b, v5
	v_mul_f32_e32 v6, 0xbfb8aa3b, v6
	v_mul_f32_e32 v7, 0xbfb8aa3b, v7
	v_mul_f32_e32 v8, 0xbfb8aa3b, v8
	v_exp_f32_e32 v4, v4
	v_mul_f32_e32 v9, 0xbfb8aa3b, v9
	v_exp_f32_e32 v5, v5
	v_mul_f32_e32 v10, 0xbfb8aa3b, v10
	v_exp_f32_e32 v6, v6
	v_mul_f32_e32 v11, 0xbfb8aa3b, v11
	v_exp_f32_e32 v7, v7
	v_exp_f32_e32 v8, v8
	v_exp_f32_e32 v9, v9
	v_exp_f32_e32 v10, v10
	v_exp_f32_e32 v11, v11
	v_add_f32_e32 v4, 1.0, v4
	v_add_f32_e32 v5, 1.0, v5
	v_add_f32_e32 v6, 1.0, v6
	v_add_f32_e32 v7, 1.0, v7
	v_add_f32_e32 v8, 1.0, v8
	v_rcp_f32_e32 v4, v4
	v_add_f32_e32 v9, 1.0, v9
	v_rcp_f32_e32 v5, v5
	v_add_f32_e32 v10, 1.0, v10
	v_rcp_f32_e32 v6, v6
	v_add_f32_e32 v11, 1.0, v11
	v_rcp_f32_e32 v7, v7
	v_rcp_f32_e32 v8, v8
	v_rcp_f32_e32 v9, v9
	v_rcp_f32_e32 v10, v10
	v_rcp_f32_e32 v11, v11
	v_mul_f32_e32 v4, v67, v4
	v_mul_f32_e32 v5, v69, v5
	v_mul_f32_e32 v6, v71, v6
	v_mul_f32_e32 v7, v73, v7
	v_mul_f32_e32 v8, v66, v8
	v_mul_f32_e32 v9, v68, v9
	v_mul_f32_e32 v10, v70, v10
	v_mul_f32_e32 v11, v72, v11
	v_cvt_pk_bf16_f32 v4, v8, v4
	v_cvt_pk_bf16_f32 v5, v9, v5
	v_cvt_pk_bf16_f32 v6, v10, v6
	v_cvt_pk_bf16_f32 v7, v11, v7
	global_store_dwordx4 v[0:1], v[4:7], off sc1
	s_waitcnt vmcnt(14)
	s_nop 1
	v_mov_b32_e32 v2, v208
	v_mov_b32_e32 v3, v209
	v_mov_b32_e32 v4, v210
	v_mov_b32_e32 v5, v211
	global_load_dwordx4 v[208:211], v[250:251], off offset:2304
	v_lshlrev_b32_e32 v8, 16, v4
	v_lshlrev_b32_e32 v6, 16, v2
	v_and_b32_e32 v2, 0xffff0000, v2
	v_lshlrev_b32_e32 v7, 16, v3
	v_and_b32_e32 v3, 0xffff0000, v3
	v_and_b32_e32 v4, 0xffff0000, v4
	v_lshlrev_b32_e32 v9, 16, v5
	v_and_b32_e32 v5, 0xffff0000, v5
	v_mul_f32_e32 v2, 0xbfb8aa3b, v2
	v_mul_f32_e32 v3, 0xbfb8aa3b, v3
	v_mul_f32_e32 v4, 0xbfb8aa3b, v4
	v_mul_f32_e32 v5, 0xbfb8aa3b, v5
	v_mul_f32_e32 v6, 0xbfb8aa3b, v6
	v_exp_f32_e32 v2, v2
	v_mul_f32_e32 v7, 0xbfb8aa3b, v7
	v_exp_f32_e32 v3, v3
	v_mul_f32_e32 v8, 0xbfb8aa3b, v8
	v_exp_f32_e32 v4, v4
	v_mul_f32_e32 v9, 0xbfb8aa3b, v9
	v_exp_f32_e32 v5, v5
	v_exp_f32_e32 v6, v6
	v_exp_f32_e32 v7, v7
	v_exp_f32_e32 v8, v8
	v_exp_f32_e32 v9, v9
	v_add_f32_e32 v2, 1.0, v2
	v_add_f32_e32 v3, 1.0, v3
	v_add_f32_e32 v4, 1.0, v4
	v_add_f32_e32 v5, 1.0, v5
	v_add_f32_e32 v6, 1.0, v6
	v_rcp_f32_e32 v2, v2
	v_add_f32_e32 v7, 1.0, v7
	v_rcp_f32_e32 v3, v3
	v_add_f32_e32 v8, 1.0, v8
	v_rcp_f32_e32 v4, v4
	v_add_f32_e32 v9, 1.0, v9
	v_rcp_f32_e32 v5, v5
	v_rcp_f32_e32 v6, v6
	v_rcp_f32_e32 v7, v7
	v_rcp_f32_e32 v8, v8
	v_rcp_f32_e32 v9, v9
	v_mul_f32_e32 v2, v75, v2
	v_mul_f32_e32 v3, v77, v3
	v_mul_f32_e32 v4, v79, v4
	v_mul_f32_e32 v5, v81, v5
	v_mul_f32_e32 v6, v74, v6
	v_mul_f32_e32 v7, v76, v7
	v_mul_f32_e32 v8, v78, v8
	v_mul_f32_e32 v9, v80, v9
	v_cvt_pk_bf16_f32 v2, v6, v2
	v_cvt_pk_bf16_f32 v3, v7, v3
	v_cvt_pk_bf16_f32 v4, v8, v4
	v_cvt_pk_bf16_f32 v5, v9, v5
	global_store_dwordx4 v[0:1], v[2:5], off offset:256 sc1
	v_add_u32_e32 v0, 0x80, v134
	v_ashrrev_i32_e32 v1, 31, v0
	v_lshlrev_b64 v[2:3], 12, v[0:1]
	v_lshl_add_u64 v[2:3], s[14:15], 0, v[2:3]
	v_lshl_add_u64 v[2:3], v[2:3], 0, v[130:131]
	s_waitcnt vmcnt(15)
; __device__ __forceinline__ unsigned cvt_pk_bf16(float lo, float hi) { unsigned r; asm volatile("v_cvt_pk_bf16_f32 %0, %1, %2" : "=v"(r) : "v"(lo), "v"(hi)); return r; }
; __device__ __forceinline__ float bflo(unsigned w) { return __uint_as_float(w << 16); }
; __device__ __forceinline__ float bfhi(unsigned w) { return __uint_as_float(w & 0xffff0000u); }
;     __device__ __forceinline__ void operator()(const f32x4 (&acc)[2][2][4][2], const Unit& u, int wr, int wc, int fr, int fq) const {
;     ...
;             for (int m = 0; m < 4; ++m) { const size_t r = (size_t)(row0 + ai * HALF + m * 16);
; #pragma unroll
;                 for (int bj = 0; bj < 2; ++bj) { const u32x4 lb = *(const u32x4*)(GL + r * 2048 + 1024 + col0 + bj * HALF); float o[8];
; #pragma unroll
;                     for (int n = 0; n < 2; ++n)
; #pragma unroll
;                         for (int j = 0; j < 4; ++j) { const int e = n * 4 + j; const unsigned wb = lb[e >> 1]; const float b = (e & 1) ? bfhi(wb) : bflo(wb);
;                             o[e] = acc[ai][bj][m][n][j] * __builtin_amdgcn_rcpf(1.0f + __expf(-b)); }
;                     u32x4 w; w.x = cvt_pk_bf16(o[0], o[1]); w.y = cvt_pk_bf16(o[2], o[3]); w.z = cvt_pk_bf16(o[4], o[5]); w.w = cvt_pk_bf16(o[6], o[7]);
;                     *(u32x4*)(gout + r * 1024 + col0 + bj * HALF) = w; asm volatile("" ::: "memory"); } }
	s_nop 1
	v_mov_b32_e32 v4, v180
	v_mov_b32_e32 v5, v181
	v_mov_b32_e32 v6, v182
	v_mov_b32_e32 v7, v183
	v_lshlrev_b64 v[0:1], 11, v[0:1]
	v_lshl_add_u64 v[0:1], v[132:133], 0, v[0:1]
	v_lshlrev_b32_e32 v8, 16, v4
	v_and_b32_e32 v4, 0xffff0000, v4
	v_lshlrev_b32_e32 v9, 16, v5
	v_and_b32_e32 v5, 0xffff0000, v5
	v_lshlrev_b32_e32 v10, 16, v6
	v_and_b32_e32 v6, 0xffff0000, v6
	v_lshlrev_b32_e32 v11, 16, v7
	v_and_b32_e32 v7, 0xffff0000, v7
	v_mul_f32_e32 v4, 0xbfb8aa3b, v4
	v_mul_f32_e32 v5, 0xbfb8aa3b, v5
	v_mul_f32_e32 v6, 0xbfb8aa3b, v6
	v_mul_f32_e32 v7, 0xbfb8aa3b, v7
	v_mul_f32_e32 v8, 0xbfb8aa3b, v8
	v_exp_f32_e32 v4, v4
	v_mul_f32_e32 v9, 0xbfb8aa3b, v9
	v_exp_f32_e32 v5, v5
	v_mul_f32_e32 v10, 0xbfb8aa3b, v10
	v_exp_f32_e32 v6, v6
	v_mul_f32_e32 v11, 0xbfb8aa3b, v11
	v_exp_f32_e32 v7, v7
	v_exp_f32_e32 v8, v8
	v_exp_f32_e32 v9, v9
	v_exp_f32_e32 v10, v10
	v_exp_f32_e32 v11, v11
	v_add_f32_e32 v4, 1.0, v4
	v_add_f32_e32 v5, 1.0, v5
	v_add_f32_e32 v6, 1.0, v6
	v_add_f32_e32 v7, 1.0, v7
	v_add_f32_e32 v8, 1.0, v8
	v_rcp_f32_e32 v4, v4
	v_add_f32_e32 v9, 1.0, v9
	v_rcp_f32_e32 v5, v5
	v_add_f32_e32 v10, 1.0, v10
	v_rcp_f32_e32 v6, v6
	v_add_f32_e32 v11, 1.0, v11
	v_rcp_f32_e32 v7, v7
	v_rcp_f32_e32 v8, v8
	v_rcp_f32_e32 v9, v9
	v_rcp_f32_e32 v10, v10
	v_rcp_f32_e32 v11, v11
	v_mul_f32_e32 v4, v83, v4
	v_mul_f32_e32 v5, v85, v5
	v_mul_f32_e32 v6, v87, v6
	v_mul_f32_e32 v7, v89, v7
	v_mul_f32_e32 v8, v82, v8
	v_mul_f32_e32 v9, v84, v9
	v_mul_f32_e32 v10, v86, v10
	v_mul_f32_e32 v11, v88, v11
	v_cvt_pk_bf16_f32 v4, v8, v4
	v_cvt_pk_bf16_f32 v5, v9, v5
	v_cvt_pk_bf16_f32 v6, v10, v6
	v_cvt_pk_bf16_f32 v7, v11, v7
	global_store_dwordx4 v[0:1], v[4:7], off sc1
	s_waitcnt vmcnt(14)
	s_nop 1
	v_mov_b32_e32 v2, v184
	v_mov_b32_e32 v3, v185
	v_mov_b32_e32 v4, v186
	v_mov_b32_e32 v5, v187
	v_lshlrev_b32_e32 v8, 16, v4
	v_lshlrev_b32_e32 v6, 16, v2
	v_and_b32_e32 v2, 0xffff0000, v2
	v_lshlrev_b32_e32 v7, 16, v3
	v_and_b32_e32 v3, 0xffff0000, v3
	v_and_b32_e32 v4, 0xffff0000, v4
	v_lshlrev_b32_e32 v9, 16, v5
	v_and_b32_e32 v5, 0xffff0000, v5
	v_mul_f32_e32 v2, 0xbfb8aa3b, v2
	v_mul_f32_e32 v3, 0xbfb8aa3b, v3
	v_mul_f32_e32 v4, 0xbfb8aa3b, v4
	v_mul_f32_e32 v5, 0xbfb8aa3b, v5
	v_mul_f32_e32 v6, 0xbfb8aa3b, v6
	v_exp_f32_e32 v2, v2
	v_mul_f32_e32 v7, 0xbfb8aa3b, v7
	v_exp_f32_e32 v3, v3
	v_mul_f32_e32 v8, 0xbfb8aa3b, v8
	v_exp_f32_e32 v4, v4
	v_mul_f32_e32 v9, 0xbfb8aa3b, v9
	v_exp_f32_e32 v5, v5
	v_exp_f32_e32 v6, v6
	v_exp_f32_e32 v7, v7
	v_exp_f32_e32 v8, v8
	v_exp_f32_e32 v9, v9
	v_add_f32_e32 v2, 1.0, v2
	v_add_f32_e32 v3, 1.0, v3
	v_add_f32_e32 v4, 1.0, v4
	v_add_f32_e32 v5, 1.0, v5
	v_add_f32_e32 v6, 1.0, v6
	v_rcp_f32_e32 v2, v2
	v_add_f32_e32 v7, 1.0, v7
	v_rcp_f32_e32 v3, v3
	v_add_f32_e32 v8, 1.0, v8
	v_rcp_f32_e32 v4, v4
	v_add_f32_e32 v9, 1.0, v9
	v_rcp_f32_e32 v5, v5
	v_rcp_f32_e32 v6, v6
	v_rcp_f32_e32 v7, v7
	v_rcp_f32_e32 v8, v8
	v_rcp_f32_e32 v9, v9
	v_mul_f32_e32 v2, v91, v2
	v_mul_f32_e32 v3, v93, v3
	v_mul_f32_e32 v4, v95, v4
	v_mul_f32_e32 v5, v97, v5
	v_mul_f32_e32 v6, v90, v6
	v_mul_f32_e32 v7, v92, v7
	v_mul_f32_e32 v8, v94, v8
	v_mul_f32_e32 v9, v96, v9
	v_cvt_pk_bf16_f32 v2, v6, v2
	v_cvt_pk_bf16_f32 v3, v7, v3
	v_cvt_pk_bf16_f32 v4, v8, v4
	v_cvt_pk_bf16_f32 v5, v9, v5
	global_store_dwordx4 v[0:1], v[2:5], off offset:256 sc1
	v_add_u32_e32 v0, 0x90, v134
	v_ashrrev_i32_e32 v1, 31, v0
	v_lshlrev_b64 v[2:3], 12, v[0:1]
	v_lshl_add_u64 v[2:3], s[14:15], 0, v[2:3]
	v_lshl_add_u64 v[2:3], v[2:3], 0, v[130:131]
	s_waitcnt vmcnt(13)
	s_nop 1
	v_mov_b32_e32 v4, v188
	v_mov_b32_e32 v5, v189
	v_mov_b32_e32 v6, v190
	v_mov_b32_e32 v7, v191
	v_lshlrev_b64 v[0:1], 11, v[0:1]
	v_lshl_add_u64 v[0:1], v[132:133], 0, v[0:1]
	v_lshlrev_b32_e32 v8, 16, v4
	v_and_b32_e32 v4, 0xffff0000, v4
	v_lshlrev_b32_e32 v9, 16, v5
	v_and_b32_e32 v5, 0xffff0000, v5
	v_lshlrev_b32_e32 v10, 16, v6
	v_and_b32_e32 v6, 0xffff0000, v6
	v_lshlrev_b32_e32 v11, 16, v7
	v_and_b32_e32 v7, 0xffff0000, v7
	v_mul_f32_e32 v4, 0xbfb8aa3b, v4
	v_mul_f32_e32 v5, 0xbfb8aa3b, v5
	v_mul_f32_e32 v6, 0xbfb8aa3b, v6
	v_mul_f32_e32 v7, 0xbfb8aa3b, v7
	v_mul_f32_e32 v8, 0xbfb8aa3b, v8
	v_exp_f32_e32 v4, v4
	v_mul_f32_e32 v9, 0xbfb8aa3b, v9
	v_exp_f32_e32 v5, v5
	v_mul_f32_e32 v10, 0xbfb8aa3b, v10
	v_exp_f32_e32 v6, v6
	v_mul_f32_e32 v11, 0xbfb8aa3b, v11
	v_exp_f32_e32 v7, v7
	v_exp_f32_e32 v8, v8
	v_exp_f32_e32 v9, v9
	v_exp_f32_e32 v10, v10
	v_exp_f32_e32 v11, v11
	v_add_f32_e32 v4, 1.0, v4
	v_add_f32_e32 v5, 1.0, v5
	v_add_f32_e32 v6, 1.0, v6
	v_add_f32_e32 v7, 1.0, v7
	v_add_f32_e32 v8, 1.0, v8
	v_rcp_f32_e32 v4, v4
	v_add_f32_e32 v9, 1.0, v9
	v_rcp_f32_e32 v5, v5
	v_add_f32_e32 v10, 1.0, v10
	v_rcp_f32_e32 v6, v6
	v_add_f32_e32 v11, 1.0, v11
	v_rcp_f32_e32 v7, v7
	v_rcp_f32_e32 v8, v8
	v_rcp_f32_e32 v9, v9
	v_rcp_f32_e32 v10, v10
	v_rcp_f32_e32 v11, v11
	v_mul_f32_e32 v4, v107, v4
	v_mul_f32_e32 v5, v109, v5
	v_mul_f32_e32 v6, v115, v6
	v_mul_f32_e32 v7, v117, v7
	v_mul_f32_e32 v8, v106, v8
	v_mul_f32_e32 v9, v108, v9
	v_mul_f32_e32 v10, v114, v10
	v_mul_f32_e32 v11, v116, v11
	v_cvt_pk_bf16_f32 v4, v8, v4
	v_cvt_pk_bf16_f32 v5, v9, v5
	v_cvt_pk_bf16_f32 v6, v10, v6
	v_cvt_pk_bf16_f32 v7, v11, v7
	global_store_dwordx4 v[0:1], v[4:7], off sc1
	s_waitcnt vmcnt(12)
; __device__ __forceinline__ unsigned cvt_pk_bf16(float lo, float hi) { unsigned r; asm volatile("v_cvt_pk_bf16_f32 %0, %1, %2" : "=v"(r) : "v"(lo), "v"(hi)); return r; }
; __device__ __forceinline__ float bflo(unsigned w) { return __uint_as_float(w << 16); }
; __device__ __forceinline__ float bfhi(unsigned w) { return __uint_as_float(w & 0xffff0000u); }
;     __device__ __forceinline__ void operator()(const f32x4 (&acc)[2][2][4][2], const Unit& u, int wr, int wc, int fr, int fq) const {
;     ...
;             for (int m = 0; m < 4; ++m) { const size_t r = (size_t)(row0 + ai * HALF + m * 16);
; #pragma unroll
;                 for (int bj = 0; bj < 2; ++bj) { const u32x4 lb = *(const u32x4*)(GL + r * 2048 + 1024 + col0 + bj * HALF); float o[8];
; #pragma unroll
;                     for (int n = 0; n < 2; ++n)
; #pragma unroll
;                         for (int j = 0; j < 4; ++j) { const int e = n * 4 + j; const unsigned wb = lb[e >> 1]; const float b = (e & 1) ? bfhi(wb) : bflo(wb);
;                             o[e] = acc[ai][bj][m][n][j] * __builtin_amdgcn_rcpf(1.0f + __expf(-b)); }
;                     u32x4 w; w.x = cvt_pk_bf16(o[0], o[1]); w.y = cvt_pk_bf16(o[2], o[3]); w.z = cvt_pk_bf16(o[4], o[5]); w.w = cvt_pk_bf16(o[6], o[7]);
;                     *(u32x4*)(gout + r * 1024 + col0 + bj * HALF) = w; asm volatile("" ::: "memory"); } }
	s_nop 1
	v_mov_b32_e32 v2, v192
	v_mov_b32_e32 v3, v193
	v_mov_b32_e32 v4, v194
	v_mov_b32_e32 v5, v195
	v_lshlrev_b32_e32 v8, 16, v4
	v_lshlrev_b32_e32 v6, 16, v2
	v_and_b32_e32 v2, 0xffff0000, v2
	v_lshlrev_b32_e32 v7, 16, v3
	v_and_b32_e32 v3, 0xffff0000, v3
	v_and_b32_e32 v4, 0xffff0000, v4
	v_lshlrev_b32_e32 v9, 16, v5
	v_and_b32_e32 v5, 0xffff0000, v5
	v_mul_f32_e32 v2, 0xbfb8aa3b, v2
	v_mul_f32_e32 v3, 0xbfb8aa3b, v3
	v_mul_f32_e32 v4, 0xbfb8aa3b, v4
	v_mul_f32_e32 v5, 0xbfb8aa3b, v5
	v_mul_f32_e32 v6, 0xbfb8aa3b, v6
	v_exp_f32_e32 v2, v2
	v_mul_f32_e32 v7, 0xbfb8aa3b, v7
	v_exp_f32_e32 v3, v3
	v_mul_f32_e32 v8, 0xbfb8aa3b, v8
	v_exp_f32_e32 v4, v4
	v_mul_f32_e32 v9, 0xbfb8aa3b, v9
	v_exp_f32_e32 v5, v5
	v_exp_f32_e32 v6, v6
	v_exp_f32_e32 v7, v7
	v_exp_f32_e32 v8, v8
	v_exp_f32_e32 v9, v9
	v_add_f32_e32 v2, 1.0, v2
	v_add_f32_e32 v3, 1.0, v3
	v_add_f32_e32 v4, 1.0, v4
	v_add_f32_e32 v5, 1.0, v5
	v_add_f32_e32 v6, 1.0, v6
	v_rcp_f32_e32 v2, v2
	v_add_f32_e32 v7, 1.0, v7
	v_rcp_f32_e32 v3, v3
	v_add_f32_e32 v8, 1.0, v8
	v_rcp_f32_e32 v4, v4
	v_add_f32_e32 v9, 1.0, v9
	v_rcp_f32_e32 v5, v5
	v_rcp_f32_e32 v6, v6
	v_rcp_f32_e32 v7, v7
	v_rcp_f32_e32 v8, v8
	v_rcp_f32_e32 v9, v9
	v_mul_f32_e32 v2, v119, v2
	v_mul_f32_e32 v3, v121, v3
	v_mul_f32_e32 v4, v123, v4
	v_mul_f32_e32 v5, v125, v5
	v_mul_f32_e32 v6, v118, v6
	v_mul_f32_e32 v7, v120, v7
	v_mul_f32_e32 v8, v122, v8
	v_mul_f32_e32 v9, v124, v9
	v_cvt_pk_bf16_f32 v2, v6, v2
	v_cvt_pk_bf16_f32 v3, v7, v3
	v_cvt_pk_bf16_f32 v4, v8, v4
	v_cvt_pk_bf16_f32 v5, v9, v5
	global_store_dwordx4 v[0:1], v[2:5], off offset:256 sc1
	v_add_u32_e32 v0, 0xa0, v134
	v_ashrrev_i32_e32 v1, 31, v0
	v_lshlrev_b64 v[2:3], 12, v[0:1]
	v_lshl_add_u64 v[2:3], s[14:15], 0, v[2:3]
	v_lshl_add_u64 v[2:3], v[2:3], 0, v[130:131]
	s_waitcnt vmcnt(11)
	s_nop 1
	v_mov_b32_e32 v4, v196
	v_mov_b32_e32 v5, v197
	v_mov_b32_e32 v6, v198
	v_mov_b32_e32 v7, v199
	v_lshlrev_b64 v[0:1], 11, v[0:1]
	v_lshl_add_u64 v[0:1], v[132:133], 0, v[0:1]
	v_lshlrev_b32_e32 v8, 16, v4
	v_and_b32_e32 v4, 0xffff0000, v4
	v_lshlrev_b32_e32 v9, 16, v5
	v_and_b32_e32 v5, 0xffff0000, v5
	v_lshlrev_b32_e32 v10, 16, v6
	v_and_b32_e32 v6, 0xffff0000, v6
	v_lshlrev_b32_e32 v11, 16, v7
	v_and_b32_e32 v7, 0xffff0000, v7
	v_mul_f32_e32 v4, 0xbfb8aa3b, v4
	v_mul_f32_e32 v5, 0xbfb8aa3b, v5
	v_mul_f32_e32 v6, 0xbfb8aa3b, v6
	v_mul_f32_e32 v7, 0xbfb8aa3b, v7
	v_mul_f32_e32 v8, 0xbfb8aa3b, v8
	v_exp_f32_e32 v4, v4
	v_mul_f32_e32 v9, 0xbfb8aa3b, v9
	v_exp_f32_e32 v5, v5
	v_mul_f32_e32 v10, 0xbfb8aa3b, v10
	v_exp_f32_e32 v6, v6
	v_mul_f32_e32 v11, 0xbfb8aa3b, v11
	v_exp_f32_e32 v7, v7
	v_exp_f32_e32 v8, v8
	v_exp_f32_e32 v9, v9
	v_exp_f32_e32 v10, v10
	v_exp_f32_e32 v11, v11
	v_add_f32_e32 v4, 1.0, v4
	v_add_f32_e32 v5, 1.0, v5
	v_add_f32_e32 v6, 1.0, v6
	v_add_f32_e32 v7, 1.0, v7
	v_add_f32_e32 v8, 1.0, v8
	v_rcp_f32_e32 v4, v4
	v_add_f32_e32 v9, 1.0, v9
	v_rcp_f32_e32 v5, v5
	v_add_f32_e32 v10, 1.0, v10
	v_rcp_f32_e32 v6, v6
	v_add_f32_e32 v11, 1.0, v11
	v_rcp_f32_e32 v7, v7
	v_rcp_f32_e32 v8, v8
	v_rcp_f32_e32 v9, v9
	v_rcp_f32_e32 v10, v10
	v_rcp_f32_e32 v11, v11
	v_mul_f32_e32 v4, v127, v4
	v_mul_f32_e32 v5, v129, v5
	v_mul_f32_e32 v6, v111, v6
	v_mul_f32_e32 v7, v113, v7
	v_mul_f32_e32 v8, v126, v8
	v_mul_f32_e32 v9, v128, v9
	v_mul_f32_e32 v10, v110, v10
	v_mul_f32_e32 v11, v112, v11
	v_cvt_pk_bf16_f32 v4, v8, v4
	v_cvt_pk_bf16_f32 v5, v9, v5
	v_cvt_pk_bf16_f32 v6, v10, v6
	v_cvt_pk_bf16_f32 v7, v11, v7
	global_store_dwordx4 v[0:1], v[4:7], off sc1
	s_waitcnt vmcnt(10)
; __device__ __forceinline__ unsigned cvt_pk_bf16(float lo, float hi) { unsigned r; asm volatile("v_cvt_pk_bf16_f32 %0, %1, %2" : "=v"(r) : "v"(lo), "v"(hi)); return r; }
; __device__ __forceinline__ float bflo(unsigned w) { return __uint_as_float(w << 16); }
; __device__ __forceinline__ float bfhi(unsigned w) { return __uint_as_float(w & 0xffff0000u); }
; #define PG8_BAR __builtin_amdgcn_s_barrier()
; template <bool CHAIN, class Epi, class Sched>
; __device__ __forceinline__ void gemm_phase(LAS unsigned char* lds, const int tid, const int K, const int lda, const int ldb, const Sched& S, const Epi& E) {
;     ...
;         if (!has_next) break;
; #pragma unroll
;         for (int a = 0; a < 2; ++a)
; #pragma unroll
;             for (int b = 0; b < 2; ++b)
; #pragma unroll
;                 for (int m = 0; m < 4; ++m)
; #pragma unroll
;                     for (int n = 0; n < 2; ++n) acc[a][b][m][n] = (f32x4){0.f, 0.f, 0.f, 0.f};
;         cur = nxt; ++ui;
;         if (wr == 1) PG8_BAR;
;     __device__ __forceinline__ void operator()(const f32x4 (&acc)[2][2][4][2], const Unit& u, int wr, int wc, int fr, int fq) const {
;     ...
;             for (int m = 0; m < 4; ++m) { const size_t r = (size_t)(row0 + ai * HALF + m * 16);
; #pragma unroll
;                 for (int bj = 0; bj < 2; ++bj) { const u32x4 lb = *(const u32x4*)(GL + r * 2048 + 1024 + col0 + bj * HALF); float o[8];
; #pragma unroll
;                     for (int n = 0; n < 2; ++n)
; #pragma unroll
;                         for (int j = 0; j < 4; ++j) { const int e = n * 4 + j; const unsigned wb = lb[e >> 1]; const float b = (e & 1) ? bfhi(wb) : bflo(wb);
;                             o[e] = acc[ai][bj][m][n][j] * __builtin_amdgcn_rcpf(1.0f + __expf(-b)); }
;                     u32x4 w; w.x = cvt_pk_bf16(o[0], o[1]); w.y = cvt_pk_bf16(o[2], o[3]); w.z = cvt_pk_bf16(o[4], o[5]); w.w = cvt_pk_bf16(o[6], o[7]);
;                     *(u32x4*)(gout + r * 1024 + col0 + bj * HALF) = w; asm volatile("" ::: "memory"); } }
;     }
	s_nop 1
	v_mov_b32_e32 v2, v200
	v_mov_b32_e32 v3, v201
	v_mov_b32_e32 v4, v202
	v_mov_b32_e32 v5, v203
	v_lshlrev_b32_e32 v8, 16, v4
	v_lshlrev_b32_e32 v6, 16, v2
	v_and_b32_e32 v2, 0xffff0000, v2
	v_lshlrev_b32_e32 v7, 16, v3
	v_and_b32_e32 v3, 0xffff0000, v3
	v_and_b32_e32 v4, 0xffff0000, v4
	v_lshlrev_b32_e32 v9, 16, v5
	v_and_b32_e32 v5, 0xffff0000, v5
	v_mul_f32_e32 v2, 0xbfb8aa3b, v2
	v_mul_f32_e32 v3, 0xbfb8aa3b, v3
	v_mul_f32_e32 v4, 0xbfb8aa3b, v4
	v_mul_f32_e32 v5, 0xbfb8aa3b, v5
	v_mul_f32_e32 v6, 0xbfb8aa3b, v6
	v_exp_f32_e32 v2, v2
	v_mul_f32_e32 v7, 0xbfb8aa3b, v7
	v_exp_f32_e32 v3, v3
	v_mul_f32_e32 v8, 0xbfb8aa3b, v8
	v_exp_f32_e32 v4, v4
	v_mul_f32_e32 v9, 0xbfb8aa3b, v9
	v_exp_f32_e32 v5, v5
	v_exp_f32_e32 v6, v6
	v_exp_f32_e32 v7, v7
	v_exp_f32_e32 v8, v8
	v_exp_f32_e32 v9, v9
	v_add_f32_e32 v2, 1.0, v2
	v_add_f32_e32 v3, 1.0, v3
	v_add_f32_e32 v4, 1.0, v4
	v_add_f32_e32 v5, 1.0, v5
	v_add_f32_e32 v6, 1.0, v6
	v_rcp_f32_e32 v2, v2
	v_add_f32_e32 v7, 1.0, v7
	v_rcp_f32_e32 v3, v3
	v_add_f32_e32 v8, 1.0, v8
	v_rcp_f32_e32 v4, v4
	v_add_f32_e32 v9, 1.0, v9
	v_rcp_f32_e32 v5, v5
	v_rcp_f32_e32 v6, v6
	v_rcp_f32_e32 v7, v7
	v_rcp_f32_e32 v8, v8
	v_rcp_f32_e32 v9, v9
	v_mul_f32_e32 v2, v103, v2
	v_mul_f32_e32 v3, v105, v3
	v_mul_f32_e32 v4, v99, v4
	v_mul_f32_e32 v5, v101, v5
	v_mul_f32_e32 v6, v102, v6
	v_mul_f32_e32 v7, v104, v7
	v_mul_f32_e32 v8, v98, v8
	v_mul_f32_e32 v9, v100, v9
	v_cvt_pk_bf16_f32 v2, v6, v2
	v_cvt_pk_bf16_f32 v3, v7, v3
	v_cvt_pk_bf16_f32 v4, v8, v4
	v_cvt_pk_bf16_f32 v5, v9, v5
	global_store_dwordx4 v[0:1], v[2:5], off offset:256 sc1
	v_add_u32_e32 v0, 0xb0, v134
	v_ashrrev_i32_e32 v1, 31, v0
	v_lshlrev_b64 v[2:3], 12, v[0:1]
	v_lshl_add_u64 v[2:3], s[14:15], 0, v[2:3]
	v_lshl_add_u64 v[2:3], v[2:3], 0, v[130:131]
	s_waitcnt vmcnt(9)
	s_nop 1
	v_mov_b32_e32 v4, v204
	v_mov_b32_e32 v5, v205
	v_mov_b32_e32 v6, v206
	v_mov_b32_e32 v7, v207
	v_lshlrev_b64 v[0:1], 11, v[0:1]
	v_lshl_add_u64 v[0:1], v[132:133], 0, v[0:1]
	v_lshlrev_b32_e32 v8, 16, v4
	v_and_b32_e32 v4, 0xffff0000, v4
	v_lshlrev_b32_e32 v9, 16, v5
	v_and_b32_e32 v5, 0xffff0000, v5
	v_lshlrev_b32_e32 v10, 16, v6
	v_and_b32_e32 v6, 0xffff0000, v6
	v_lshlrev_b32_e32 v11, 16, v7
	v_and_b32_e32 v7, 0xffff0000, v7
	v_mul_f32_e32 v4, 0xbfb8aa3b, v4
	v_mul_f32_e32 v5, 0xbfb8aa3b, v5
	v_mul_f32_e32 v6, 0xbfb8aa3b, v6
	v_mul_f32_e32 v7, 0xbfb8aa3b, v7
	v_mul_f32_e32 v8, 0xbfb8aa3b, v8
	v_exp_f32_e32 v4, v4
	v_mul_f32_e32 v9, 0xbfb8aa3b, v9
	v_exp_f32_e32 v5, v5
	v_mul_f32_e32 v10, 0xbfb8aa3b, v10
	v_exp_f32_e32 v6, v6
	v_mul_f32_e32 v11, 0xbfb8aa3b, v11
	v_exp_f32_e32 v7, v7
	v_exp_f32_e32 v8, v8
	v_exp_f32_e32 v9, v9
	v_exp_f32_e32 v10, v10
	v_exp_f32_e32 v11, v11
	v_add_f32_e32 v4, 1.0, v4
	v_add_f32_e32 v5, 1.0, v5
	v_add_f32_e32 v6, 1.0, v6
	v_add_f32_e32 v7, 1.0, v7
	v_add_f32_e32 v8, 1.0, v8
	v_rcp_f32_e32 v4, v4
	v_add_f32_e32 v9, 1.0, v9
	v_rcp_f32_e32 v5, v5
	v_add_f32_e32 v10, 1.0, v10
	v_rcp_f32_e32 v6, v6
	v_add_f32_e32 v11, 1.0, v11
	v_rcp_f32_e32 v7, v7
	v_rcp_f32_e32 v8, v8
	v_rcp_f32_e32 v9, v9
	v_rcp_f32_e32 v10, v10
	v_rcp_f32_e32 v11, v11
	v_mul_f32_e32 v4, v63, v4
	v_mul_f32_e32 v5, v65, v5
	v_mul_f32_e32 v6, v43, v6
	v_mul_f32_e32 v7, v45, v7
	v_mul_f32_e32 v8, v62, v8
	v_mul_f32_e32 v9, v64, v9
	v_mul_f32_e32 v10, v42, v10
	v_mul_f32_e32 v11, v44, v11
	v_cvt_pk_bf16_f32 v4, v8, v4
	v_cvt_pk_bf16_f32 v5, v9, v5
	v_cvt_pk_bf16_f32 v6, v10, v6
	v_cvt_pk_bf16_f32 v7, v11, v7
	global_store_dwordx4 v[0:1], v[4:7], off sc1
	s_waitcnt vmcnt(8)
	s_nop 1
	v_mov_b32_e32 v2, v208
	v_mov_b32_e32 v3, v209
	v_mov_b32_e32 v4, v210
	v_mov_b32_e32 v5, v211
	v_lshlrev_b32_e32 v8, 16, v4
	v_lshlrev_b32_e32 v6, 16, v2
	v_and_b32_e32 v2, 0xffff0000, v2
	v_lshlrev_b32_e32 v7, 16, v3
	v_and_b32_e32 v3, 0xffff0000, v3
	v_and_b32_e32 v4, 0xffff0000, v4
	v_lshlrev_b32_e32 v9, 16, v5
	v_and_b32_e32 v5, 0xffff0000, v5
	v_mul_f32_e32 v2, 0xbfb8aa3b, v2
	v_mul_f32_e32 v3, 0xbfb8aa3b, v3
	v_mul_f32_e32 v4, 0xbfb8aa3b, v4
	v_mul_f32_e32 v5, 0xbfb8aa3b, v5
	v_mul_f32_e32 v6, 0xbfb8aa3b, v6
	v_exp_f32_e32 v2, v2
	v_mul_f32_e32 v7, 0xbfb8aa3b, v7
	v_exp_f32_e32 v3, v3
	v_mul_f32_e32 v8, 0xbfb8aa3b, v8
	v_exp_f32_e32 v4, v4
	v_mul_f32_e32 v9, 0xbfb8aa3b, v9
	v_exp_f32_e32 v5, v5
	v_exp_f32_e32 v6, v6
	v_exp_f32_e32 v7, v7
	v_exp_f32_e32 v8, v8
	v_exp_f32_e32 v9, v9
	v_add_f32_e32 v2, 1.0, v2
	v_add_f32_e32 v3, 1.0, v3
	v_add_f32_e32 v4, 1.0, v4
	v_add_f32_e32 v5, 1.0, v5
	v_add_f32_e32 v6, 1.0, v6
	v_rcp_f32_e32 v2, v2
	v_add_f32_e32 v7, 1.0, v7
	v_rcp_f32_e32 v3, v3
	v_add_f32_e32 v8, 1.0, v8
	v_rcp_f32_e32 v4, v4
	v_add_f32_e32 v9, 1.0, v9
	v_rcp_f32_e32 v5, v5
	v_rcp_f32_e32 v6, v6
	v_rcp_f32_e32 v7, v7
	v_rcp_f32_e32 v8, v8
	v_rcp_f32_e32 v9, v9
	v_mul_f32_e32 v2, v39, v2
	v_mul_f32_e32 v3, v41, v3
	v_mul_f32_e32 v4, v35, v4
	v_mul_f32_e32 v5, v37, v5
	v_mul_f32_e32 v6, v38, v6
	v_mul_f32_e32 v7, v40, v7
	v_mul_f32_e32 v8, v34, v8
	v_mul_f32_e32 v9, v36, v9
	v_cvt_pk_bf16_f32 v2, v6, v2
	v_cvt_pk_bf16_f32 v3, v7, v3
	v_cvt_pk_bf16_f32 v4, v8, v4
	v_cvt_pk_bf16_f32 v5, v9, v5
	global_store_dwordx4 v[0:1], v[2:5], off offset:256 sc1
	s_cbranch_vccnz .LBB0_360
	s_and_b64 vcc, exec, s[42:43]
	s_cbranch_vccnz .LBB0_359
	s_barrier
	s_branch .LBB0_359
